# mixer-B: running-max shift folded into the QK MFMA accumulator init (Q fragments parked in LDS), per-element subtract only on the rare rescale path
# speedup vs baseline: 1.0043x; 1.0013x over previous
; #define LAS __attribute__((address_space(3)))
; __device__ __forceinline__ void partialSM(f32x16& p0, f32x16& p1, const LAS float* tbp, int relc, float cL, float cR, float& m_reg, float& mn, float& alpha) {
;     float cb = 0.f;
;     if (relc + 63 <= -559) cb = cL;
;     else if (relc - 31 >= 559) cb = cR;
;     else {
; #pragma unroll
;         for (int r = 0; r < 16; ++r) { p0[r] += tbp[(r & 3) + 8 * (r >> 2)]; p1[r] += tbp[32 + (r & 3) + 8 * (r >> 2)]; }
;     }
;     float pmax = p0[0];
; #pragma unroll
;     for (int r = 1; r < 16; ++r) pmax = fmaxf(pmax, p0[r]);
; #pragma unroll
;     for (int r = 0; r < 16; ++r) pmax = fmaxf(pmax, p1[r]);
;     pmax = half_max(pmax) + cb;
;     if (__builtin_expect(__all(pmax - m_reg <= 8.f), 1)) { mn = m_reg; alpha = 1.f; }
;     else { mn = fmaxf(m_reg, pmax); alpha = __builtin_amdgcn_exp2f(m_reg - mn); m_reg = mn; }
;     const float sh = mn - cb;
; #pragma unroll
;     for (int r = 0; r < 16; ++r) { p0[r] -= sh; p1[r] -= sh; }
; #pragma unroll
;     for (int r = 0; r < 16; ++r) p0[r] = __builtin_amdgcn_exp2f(p0[r]);
; }
; __device__ __forceinline__ void unit(LAS unsigned char* lds, const bf16* __restrict__ PROJ, bf16* __restrict__ MIXED, const float* __restrict__ subln_g, float lam, int R0, int seq, int h, int qb) {
;     ...
;     float m_reg = -1e30f, l_reg = 0.f; f32x16 o[4]; bf16x8 qr[4];
; #pragma unroll
;     for (int d = 0; d < 4; ++d)
; #pragma unroll
;         for (int i = 0; i < 16; ++i) o[d][i] = 0.f;
;     const int qrow = 128 * qb + 32 * g + r32;
;     const bf16* Qw = PROJ + (size_t)(R0 + qrow) * PW + 3072 + h * 128 + c * 64 + hi * 8;
; #pragma unroll
;     for (int d0 = 0; d0 < 4; ++d0) qr[d0] = *(const bf16x8*)(Qw + d0 * 16);
;     const bf16* Kh = PROJ + (size_t)R0 * PW + 4096 + h * 128; const bf16* Vh = PROJ + (size_t)R0 * PW + 5120 + h * 128;
;     const int sr = tid >> 4, sc = (tid & 15) * 8, vst0 = v_st(sr, sc), vst1 = v_st(32 + sr, sc);
;     const int vb0 = (int)(uintptr_t)V_lds + v_rd_base(lane);
;     const int cb0 = (c * 64 + hi * 8) * 2;
;     const LAS float* tbq = tb + (4095 - qrow + 4 * hi);
;     const int rc0 = -(128 * qb + 32 * g);
;     const float cL = tb[0], cR = tb[8190];
;     struct { bf16x8 vs0, vs1, ks0, ks1; } sr_[2];
;     ...
;     f32x16 pA0, pA1, pB0, pB1; float mnA, mnB, alA, alB; bf16x8 pa0, pa1, pa2, pa3; const int NT = seq / 64;
;     constexpr int SE = 0, SO = 1;
.LBB0_259:
	v_add_co_u32_e32 v38, vcc, s54, v32
	s_nop 6
	v_max_f32_e32 v58, v1, v1
	v_addc_co_u32_e32 v39, vcc, 0, v33, vcc
	v_add_co_u32_e32 v42, vcc, s55, v32
	v_max_f32_e32 v59, v0, v0
	s_nop 0
	v_addc_co_u32_e32 v43, vcc, 0, v33, vcc
	v_add_co_u32_e32 v46, vcc, s54, v34
	global_load_dwordx4 v[38:41], v[38:39], off
	s_nop 0
	global_load_dwordx4 v[42:45], v[42:43], off
	v_addc_co_u32_e32 v47, vcc, 0, v35, vcc
	v_add_co_u32_e32 v50, vcc, s55, v34
	v_max_f32_e32 v58, v59, v58
	s_nop 0
	v_addc_co_u32_e32 v51, vcc, 0, v35, vcc
	v_add_co_u32_e32 v54, vcc, s56, v34
	global_load_dwordx4 v[46:49], v[46:47], off
	s_nop 0
	global_load_dwordx4 v[50:53], v[50:51], off
	v_addc_co_u32_e32 v55, vcc, 0, v35, vcc
	v_add_co_u32_e32 v34, vcc, s57, v34
	s_and_b32 s4, s33, 0x3fffffc0
	s_nop 0
	v_addc_co_u32_e32 v35, vcc, 0, v35, vcc
	v_add_co_u32_e32 v56, vcc, s56, v32
	s_lshl_b32 s4, s4, 2
	s_nop 0
	v_addc_co_u32_e32 v57, vcc, 0, v33, vcc
	v_add_co_u32_e32 v32, vcc, s57, v32
	s_add_i32 s4, s4, 0
	s_nop 0
	v_addc_co_u32_e32 v33, vcc, 0, v33, vcc
	global_load_dwordx4 v[116:119], v[54:55], off
	global_load_dwordx4 v[112:115], v[34:35], off
	global_load_dwordx4 v[124:127], v[56:57], off
	global_load_dwordx4 v[120:123], v[32:33], off
	v_max3_f32 v32, v58, v2, v3
	v_max3_f32 v32, v32, v4, v5
	v_max3_f32 v32, v32, v6, v7
	v_max3_f32 v32, v32, v8, v9
	v_max3_f32 v32, v32, v10, v11
	v_max3_f32 v32, v32, v12, v13
	v_max3_f32 v32, v32, v14, v15
	v_max3_f32 v32, v32, v16, v17
	v_max3_f32 v32, v32, v18, v19
	v_max3_f32 v32, v32, v20, v21
	v_max3_f32 v32, v32, v22, v23
	v_max3_f32 v32, v32, v24, v25
	v_max3_f32 v32, v32, v26, v27
	v_max3_f32 v32, v32, v28, v29
	v_max3_f32 v32, v32, v30, v31
	v_mov_b32_e32 v33, v32
	s_nop 1
	v_permlane32_swap_b32_e32 v32, v33
	v_max_f32_e32 v33, v33, v33
	v_max_f32_e32 v32, v32, v32
	v_max_f32_e32 v32, v32, v33
	v_add_f32_e32 v32, v37, v32
	v_add_f32_e32 v33, 0x7149f2ca, v32
	s_lshr_b32 s90, s96, 6
	s_add_i32 s4, s4, 0x18000
	v_cmp_ge_f32_e32 vcc, s35, v33
	s_cmp_eq_u64 vcc, exec
	v_max_f32_e32 v32, 0xf149f2ca, v32
	s_cselect_b64 vcc, -1, 0
	v_cndmask_b32_e32 v148, v32, v214, vcc
	v_sub_f32_e32 v33, v148, v37
	v_sub_f32_e32 v0, v0, v33
	v_exp_f32_e32 v145, v0
	v_sub_f32_e32 v0, v1, v33
	v_exp_f32_e32 v158, v0
	v_sub_f32_e32 v0, v2, v33
	v_exp_f32_e32 v146, v0
	v_sub_f32_e32 v0, v3, v33
	v_exp_f32_e32 v159, v0
	v_sub_f32_e32 v0, v4, v33
	v_exp_f32_e32 v147, v0
	v_sub_f32_e32 v0, v5, v33
	v_exp_f32_e32 v228, v0
	v_sub_f32_e32 v0, v6, v33
	v_exp_f32_e32 v157, v0
	v_sub_f32_e32 v0, v7, v33
	v_exp_f32_e32 v231, v0
	v_sub_f32_e32 v0, v8, v33
	v_exp_f32_e32 v149, v0
	v_sub_f32_e32 v0, v9, v33
	v_exp_f32_e32 v153, v0
	v_sub_f32_e32 v0, v10, v33
	v_exp_f32_e32 v150, v0
	v_sub_f32_e32 v0, v11, v33
	v_exp_f32_e32 v154, v0
	v_sub_f32_e32 v0, v12, v33
	v_sub_f32_e32 v140, v16, v33
	v_sub_f32_e32 v16, 0xf149f2ca, v32
	v_exp_f32_e32 v151, v0
	v_sub_f32_e32 v0, v13, v33
	v_exp_f32_e32 v16, v16
	v_exp_f32_e32 v155, v0
	v_sub_f32_e32 v0, v14, v33
	v_exp_f32_e32 v152, v0
	v_sub_f32_e32 v0, v15, v33
	v_exp_f32_e32 v156, v0
	v_lshl_add_u32 v215, v169, 2, s4
	v_lshl_add_u32 v179, v171, 2, s4
	s_lshl_b64 s[4:5], s[6:7], 8
	s_waitcnt vmcnt(4)
	s_add_u32 s4, s29, s4
	v_lshlrev_b32_e32 v0, 2, v36
	v_mov_b32_e32 v14, v161
	v_mov_b32_e32 v15, v161
	s_waitcnt vmcnt(7)
	ds_write_b128 v210, v[38:41] offset:16384
	s_waitcnt vmcnt(6)
	ds_write_b128 v211, v[42:45] offset:16384
	s_waitcnt vmcnt(5)
	ds_write_b128 v212, v[46:49] offset:49152
	s_waitcnt vmcnt(4)
	ds_write_b128 v213, v[50:53] offset:49152
	v_sub_f32_e32 v141, v17, v33
	v_sub_f32_e32 v142, v18, v33
	v_sub_f32_e32 v143, v19, v33
	v_sub_f32_e32 v130, v20, v33
	v_sub_f32_e32 v131, v21, v33
	v_sub_f32_e32 v132, v22, v33
	v_sub_f32_e32 v133, v23, v33
	v_sub_f32_e32 v134, v24, v33
	v_sub_f32_e32 v135, v25, v33
	v_sub_f32_e32 v138, v26, v33
	v_sub_f32_e32 v139, v27, v33
	v_sub_f32_e32 v128, v28, v33
	v_sub_f32_e32 v129, v29, v33
	v_sub_f32_e32 v136, v30, v33
	v_sub_f32_e32 v137, v31, v33
	v_cndmask_b32_e64 v224, v16, 1.0, vcc
	s_addc_u32 s5, s28, s5
	v_sub_u32_e32 v223, v188, v0
	v_mov_b32_e32 v0, v161
	v_mov_b32_e32 v1, v161
	v_mov_b32_e32 v2, v161
	v_mov_b32_e32 v3, v161
	v_mov_b32_e32 v4, v161
	v_mov_b32_e32 v5, v161
	v_mov_b32_e32 v6, v161
	v_mov_b32_e32 v7, v161
	v_mov_b32_e32 v8, v161
	v_mov_b32_e32 v9, v161
	v_mov_b32_e32 v10, v161
	v_mov_b32_e32 v11, v161
	v_mov_b32_e32 v12, v161
	v_mov_b32_e32 v13, v161
	v_mov_b64_e32 v[62:63], v[14:15]
	v_mov_b64_e32 v[46:47], v[14:15]
	v_mov_b64_e32 v[30:31], v[14:15]
	s_mov_b32 s33, 2
	v_lshl_add_u64 v[182:183], v[166:167], 0, s[4:5]
	s_sub_i32 s6, 64, s97
	v_mov_b32_e32 v216, 0
	v_mov_b64_e32 v[60:61], v[12:13]
	v_mov_b64_e32 v[58:59], v[10:11]
	v_mov_b64_e32 v[56:57], v[8:9]
	v_mov_b64_e32 v[54:55], v[6:7]
	v_mov_b64_e32 v[52:53], v[4:5]
	v_mov_b64_e32 v[50:51], v[2:3]
	v_mov_b64_e32 v[48:49], v[0:1]
	v_mov_b64_e32 v[44:45], v[12:13]
	v_mov_b64_e32 v[42:43], v[10:11]
	v_mov_b64_e32 v[40:41], v[8:9]
	v_mov_b64_e32 v[38:39], v[6:7]
	v_mov_b64_e32 v[36:37], v[4:5]
	v_mov_b64_e32 v[34:35], v[2:3]
	v_mov_b64_e32 v[32:33], v[0:1]
	v_mov_b64_e32 v[28:29], v[12:13]
	v_mov_b64_e32 v[26:27], v[10:11]
	v_mov_b64_e32 v[24:25], v[8:9]
	v_mov_b64_e32 v[22:23], v[6:7]
	v_mov_b64_e32 v[20:21], v[4:5]
	v_mov_b64_e32 v[18:19], v[2:3]
	v_mov_b64_e32 v[16:17], v[0:1]
	s_waitcnt lgkmcnt(0)
	s_barrier
	v_mov_b32_e32 v250, v148
	v_mov_b32_e32 v251, 1.0
	s_mov_b64 s[4:5], -1
	s_mov_b32 s29, -1
	v_lshrrev_b32_e32 v224, 6, v168
	v_and_b32_e32 v225, 63, v168
	v_lshlrev_b32_e32 v224, 12, v224
	v_lshl_add_u32 v224, v225, 4, v224
	v_add_u32_e32 v224, 0x19000, v224
	ds_write_b128 v224, v[108:111]
	ds_write_b128 v224, v[104:107] offset:1024
	ds_write_b128 v224, v[100:103] offset:2048
	ds_write_b128 v224, v[96:99] offset:3072
	v_mov_b32_e32 v232, v145
	v_mov_b32_e32 v233, v158
	v_mov_b32_e32 v234, v146
	v_mov_b32_e32 v235, v159
	v_mov_b32_e32 v236, v147
	v_mov_b32_e32 v237, v228
	v_mov_b32_e32 v238, v157
	v_mov_b32_e32 v239, v231
	v_mov_b32_e32 v240, v149
	v_mov_b32_e32 v241, v153
	v_mov_b32_e32 v242, v150
	v_mov_b32_e32 v243, v154
	v_mov_b32_e32 v244, v151
	v_mov_b32_e32 v245, v155
	v_mov_b32_e32 v246, v152
	v_mov_b32_e32 v247, v156
	v_exp_f32_e32 v144, v140
	v_exp_f32_e32 v145, v141
	v_exp_f32_e32 v146, v142
	v_exp_f32_e32 v147, v143
	v_exp_f32_e32 v148, v130
	v_exp_f32_e32 v149, v131
	v_exp_f32_e32 v150, v132
	v_exp_f32_e32 v151, v133
	v_exp_f32_e32 v152, v134
	v_exp_f32_e32 v153, v135
	v_exp_f32_e32 v154, v138
	v_exp_f32_e32 v155, v139
	v_exp_f32_e32 v156, v128
	v_exp_f32_e32 v157, v129
	v_exp_f32_e32 v158, v136
	v_exp_f32_e32 v159, v137
	s_waitcnt vmcnt(2)
	ds_write_b128 v212, v[112:115] offset:32768
	ds_write_b128 v213, v[116:119] offset:32768
	s_waitcnt lgkmcnt(0)
	s_mov_b32 s4, 0xffee0000
	s_mov_b32 s5, -1
	v_lshl_add_u64 v[112:113], v[182:183], 0, s[4:5]
	global_load_dwordx4 v[112:115], v[112:113], off offset:-2048
	s_mov_b32 s4, 0xfff40000
	v_lshl_add_u64 v[116:117], v[182:183], 0, s[4:5]
	global_load_dwordx4 v[116:119], v[116:117], off offset:-2048
; #define LAS __attribute__((address_space(3)))
; __device__ __forceinline__ void partialSM(f32x16& p0, f32x16& p1, const LAS float* tbp, int relc, float cL, float cR, float& m_reg, float& mn, float& alpha) {
;     float cb = 0.f;
;     if (relc + 63 <= -559) cb = cL;
;     else if (relc - 31 >= 559) cb = cR;
;     else {
; #pragma unroll
;         for (int r = 0; r < 16; ++r) { p0[r] += tbp[(r & 3) + 8 * (r >> 2)]; p1[r] += tbp[32 + (r & 3) + 8 * (r >> 2)]; }
;     }
;     float pmax = p0[0];
; #pragma unroll
;     for (int r = 1; r < 16; ++r) pmax = fmaxf(pmax, p0[r]);
; #pragma unroll
;     for (int r = 0; r < 16; ++r) pmax = fmaxf(pmax, p1[r]);
;     pmax = half_max(pmax) + cb;
;     if (__builtin_expect(__all(pmax - m_reg <= 8.f), 1)) { mn = m_reg; alpha = 1.f; }
;     else { mn = fmaxf(m_reg, pmax); alpha = __builtin_amdgcn_exp2f(m_reg - mn); m_reg = mn; }
;     const float sh = mn - cb;
; #pragma unroll
;     for (int r = 0; r < 16; ++r) { p0[r] -= sh; p1[r] -= sh; }
; #pragma unroll
;     for (int r = 0; r < 16; ++r) p0[r] = __builtin_amdgcn_exp2f(p0[r]);
; }
; __device__ __forceinline__ void finishSM(f32x16& p0, f32x16& p1, float alpha, float& l_reg, bf16x8& pa0, bf16x8& pa1, bf16x8& pa2, bf16x8& pa3) {
; #pragma unroll
;     for (int r = 0; r < 16; ++r) p1[r] = __builtin_amdgcn_exp2f(p1[r]);
;     float ps = 0;
; #pragma unroll
;     for (int r = 0; r < 16; ++r) ps += p0[r];
; #pragma unroll
;     for (int r = 0; r < 16; ++r) ps += p1[r];
;     ps = half_add(ps);
;     l_reg = l_reg * alpha + ps;
;     PK4(p0, 0, pa0); PK4(p0, 8, pa1); PK4(p1, 0, pa2); PK4(p1, 8, pa3);
; }
; __device__ __forceinline__ void qkt(f32x16& p0, f32x16& p1, const LAS unsigned char* Ks, const bf16x8* qr, int r32, int cb0) {
; #pragma unroll
;     for (int i = 0; i < 16; ++i) { p0[i] = 0.f; p1[i] = 0.f; }
; #pragma unroll
;     for (int d0 = 0; d0 < 4; ++d0) { const int cb = cb0 + d0 * 32;
;         const bf16x8 b0 = *(const LAS bf16x8*)(Ks + KSWZ(r32, cb));
;         const bf16x8 b1 = *(const LAS bf16x8*)(Ks + KSWZ(32 + r32, cb));
;         p0 = __builtin_amdgcn_mfma_f32_32x32x16_bf16(b0, qr[d0], p0, 0, 0, 0);
;         p1 = __builtin_amdgcn_mfma_f32_32x32x16_bf16(b1, qr[d0], p1, 0, 0, 0); }
.Lmb_loop:
	s_add_i32 s33, s33, 2
	s_cmp_ge_u32 s33, s90
	s_cselect_b64 s[26:27], -1, 0
	s_mov_b32 s28, 0
	s_cmpk_lt_i32 s6, 0xfd93
	s_cbranch_scc1 .Lmb_cls_h1
	s_mov_b32 s28, 2
	s_cmpk_gt_i32 s6, 0x24d
	s_cbranch_scc1 .Lmb_cls_h1
	s_mov_b32 s28, 1
.Lmb_cls_h1:
	s_cmp_eq_u32 s28, s29
	s_cbranch_scc1 .Lmb_nrf_h1
	s_cmp_eq_u32 s28, 0
	s_cbranch_scc0 .Lmb_rf1_h1
	v_sub_f32_e32 v96, v181, v250
	s_branch .Lmb_rf3_h1
.Lmb_rf1_h1:
	s_cmp_eq_u32 s28, 2
	s_cbranch_scc0 .Lmb_rf2_h1
	v_sub_f32_e32 v96, v217, v250
	s_branch .Lmb_rf3_h1
.Lmb_rf2_h1:
	v_sub_f32_e32 v96, 0, v250
.Lmb_rf3_h1:
	v_mov_b32_e32 v97, v96
	v_mov_b32_e32 v98, v96
	v_mov_b32_e32 v99, v96
	v_mov_b32_e32 v100, v96
	v_mov_b32_e32 v101, v96
	v_mov_b32_e32 v102, v96
	v_mov_b32_e32 v103, v96
	v_mov_b32_e32 v104, v96
	v_mov_b32_e32 v105, v96
	v_mov_b32_e32 v106, v96
	v_mov_b32_e32 v107, v96
	v_mov_b32_e32 v108, v96
	v_mov_b32_e32 v109, v96
	v_mov_b32_e32 v110, v96
	v_mov_b32_e32 v111, v96
	s_mov_b32 s29, s28
.Lmb_nrf_h1:
	ds_read_b128 v[64:67], v219 offset:49152
	ds_read_b128 v[136:139], v224
	ds_read_b128 v[68:71], v219 offset:57344
	ds_read_b128 v[128:131], v220 offset:49152
	ds_read_b128 v[132:135], v220 offset:57344
	ds_read_b128 v[140:143], v224 offset:1024
	v_add_f32_e32 v254, v232, v233
	v_add_f32_e32 v255, v234, v235
	v_add_f32_e32 v254, v254, v236
	v_add_f32_e32 v255, v255, v237
	v_add_f32_e32 v254, v254, v238
	v_add_f32_e32 v255, v255, v239
	v_add_f32_e32 v254, v254, v240
	v_add_f32_e32 v255, v255, v241
	v_add_f32_e32 v254, v254, v242
	v_add_f32_e32 v255, v255, v243
	v_add_f32_e32 v254, v254, v244
	v_add_f32_e32 v255, v255, v245
	v_add_f32_e32 v254, v254, v246
	v_add_f32_e32 v255, v255, v247
	v_add_f32_e32 v254, v254, v144
	v_add_f32_e32 v255, v255, v145
	v_add_f32_e32 v254, v254, v146
	v_add_f32_e32 v255, v255, v147
	v_add_f32_e32 v254, v254, v148
	v_add_f32_e32 v255, v255, v149
	v_add_f32_e32 v254, v254, v150
	v_add_f32_e32 v255, v255, v151
	v_add_f32_e32 v254, v254, v152
	v_add_f32_e32 v255, v255, v153
	v_add_f32_e32 v254, v254, v154
	v_add_f32_e32 v255, v255, v155
	v_add_f32_e32 v254, v254, v156
	v_add_f32_e32 v255, v255, v157
	v_add_f32_e32 v254, v254, v158
	v_add_f32_e32 v255, v255, v159
	v_add_f32_e32 v254, v254, v255
	v_mov_b32_e32 v255, v254
	s_waitcnt lgkmcnt(4)
	v_mfma_f32_32x32x16_bf16 v[80:95], v[64:67], v[136:139], v[96:111]
	v_permlane32_swap_b32_e32 v254, v255
	v_cvt_pk_bf16_f32 v232, v232, v233
	v_cvt_pk_bf16_f32 v233, v234, v235
	v_cvt_pk_bf16_f32 v234, v236, v237
	v_add_f32_e32 v254, v254, v255
	v_fma_f32 v216, v216, v251, v254
	s_waitcnt lgkmcnt(3)
	v_mfma_f32_32x32x16_bf16 v[64:79], v[68:71], v[136:139], v[96:111]
	ds_read_b128 v[136:139], v224 offset:2048
	s_and_b64 vcc, exec, s[4:5]
	s_cbranch_vccnz .Lmb_a1_h1
	v_mov_b32_e32 v251, 1.0
.Lmb_a1_h1:
	v_cvt_pk_bf16_f32 v235, v238, v239
	v_cvt_pk_bf16_f32 v236, v240, v241
	v_cvt_pk_bf16_f32 v237, v242, v243
	v_cvt_pk_bf16_f32 v238, v244, v245
	v_cvt_pk_bf16_f32 v239, v246, v247
	v_cvt_pk_bf16_f32 v144, v144, v145
	s_waitcnt lgkmcnt(1)
	v_mfma_f32_32x32x16_bf16 v[80:95], v[128:131], v[140:143], v[80:95]
	v_cvt_pk_bf16_f32 v145, v146, v147
	v_cvt_pk_bf16_f32 v146, v148, v149
	v_cvt_pk_bf16_f32 v147, v150, v151
	v_cvt_pk_bf16_f32 v148, v152, v153
	v_cvt_pk_bf16_f32 v149, v154, v155
	v_cvt_pk_bf16_f32 v150, v156, v157
	v_mfma_f32_32x32x16_bf16 v[64:79], v[132:135], v[140:143], v[64:79]
	ds_read_b128 v[128:131], v221 offset:49152
	ds_read_b128 v[132:135], v221 offset:57344
	ds_read_b128 v[140:143], v224 offset:3072
	v_cvt_pk_bf16_f32 v151, v158, v159
	ds_read_b128 v[240:243], v222 offset:49152
	ds_read_b128 v[244:247], v222 offset:57344
	s_waitcnt lgkmcnt(4)
	v_mfma_f32_32x32x16_bf16 v[80:95], v[128:131], v[136:139], v[80:95]
	v_permlane32_swap_b32_e32 v232, v234
	v_permlane32_swap_b32_e32 v233, v235
	v_permlane32_swap_b32_e32 v236, v238
	v_permlane32_swap_b32_e32 v237, v239
	s_waitcnt lgkmcnt(3)
	v_mfma_f32_32x32x16_bf16 v[64:79], v[132:135], v[136:139], v[64:79]
	v_permlane32_swap_b32_e32 v144, v146
	v_permlane32_swap_b32_e32 v145, v147
	v_permlane32_swap_b32_e32 v148, v150
	v_permlane32_swap_b32_e32 v149, v151
	s_waitcnt lgkmcnt(1)
	v_mfma_f32_32x32x16_bf16 v[80:95], v[240:243], v[140:143], v[80:95]
	s_waitcnt lgkmcnt(0)
	v_mfma_f32_32x32x16_bf16 v[64:79], v[244:247], v[140:143], v[64:79]
	s_mov_b32 s4, 0xffee0000
	s_mov_b32 s5, -1
	v_lshl_add_u64 v[128:129], v[182:183], 0, s[4:5]
	global_load_dwordx4 v[128:131], v[128:129], off
	s_mov_b32 s4, 0xfff40000
	v_lshl_add_u64 v[140:141], v[182:183], 0, s[4:5]
	global_load_dwordx4 v[140:143], v[140:141], off
	s_and_b64 vcc, exec, s[26:27]
	s_cbranch_vccnz .Lmb_skipk1
	s_mov_b32 s4, 0xfffa0000
	v_lshl_add_u64 v[132:133], v[182:183], 0, s[4:5]
	global_load_dwordx4 v[132:135], v[132:133], off offset:-2048
	global_load_dwordx4 v[136:139], v[182:183], off offset:-2048

; #define LAS __attribute__((address_space(3)))
; __device__ __forceinline__ void partialSM(f32x16& p0, f32x16& p1, const LAS float* tbp, int relc, float cL, float cR, float& m_reg, float& mn, float& alpha) {
;     float cb = 0.f;
;     if (relc + 63 <= -559) cb = cL;
;     else if (relc - 31 >= 559) cb = cR;
;     else {
; #pragma unroll
;         for (int r = 0; r < 16; ++r) { p0[r] += tbp[(r & 3) + 8 * (r >> 2)]; p1[r] += tbp[32 + (r & 3) + 8 * (r >> 2)]; }
;     }
;     float pmax = p0[0];
; #pragma unroll
;     for (int r = 1; r < 16; ++r) pmax = fmaxf(pmax, p0[r]);
; #pragma unroll
;     for (int r = 0; r < 16; ++r) pmax = fmaxf(pmax, p1[r]);
;     pmax = half_max(pmax) + cb;
;     if (__builtin_expect(__all(pmax - m_reg <= 8.f), 1)) { mn = m_reg; alpha = 1.f; }
;     else { mn = fmaxf(m_reg, pmax); alpha = __builtin_amdgcn_exp2f(m_reg - mn); m_reg = mn; }
;     const float sh = mn - cb;
; #pragma unroll
;     for (int r = 0; r < 16; ++r) { p0[r] -= sh; p1[r] -= sh; }
; #pragma unroll
;     for (int r = 0; r < 16; ++r) p0[r] = __builtin_amdgcn_exp2f(p0[r]);
; }
; template <int D0> __device__ __forceinline__ void pv_one(f32x16& od, int vb, bf16x8 pa0, bf16x8 pa1, bf16x8 pa2, bf16x8 pa3) {
;     s16x4 l0 = tr_read<v_rd_off(D0, 0, 0)>(vb), h0 = tr_read<v_rd_off(D0, 0, 1)>(vb), l1 = tr_read<v_rd_off(D0, 1, 0)>(vb), h1 = tr_read<v_rd_off(D0, 1, 1)>(vb);
;     s16x4 l2 = tr_read<v_rd_off(D0, 2, 0)>(vb), h2 = tr_read<v_rd_off(D0, 2, 1)>(vb), l3 = tr_read<v_rd_off(D0, 3, 0)>(vb), h3 = tr_read<v_rd_off(D0, 3, 1)>(vb);
;     asm volatile("s_waitcnt lgkmcnt(0)" : "+v"(l0), "+v"(h0), "+v"(l1), "+v"(h1), "+v"(l2), "+v"(h2), "+v"(l3), "+v"(h3) :: "memory");
;     od = __builtin_amdgcn_mfma_f32_32x32x16_bf16(pa0, PKV(l0, h0), od, 0, 0, 0);
;     od = __builtin_amdgcn_mfma_f32_32x32x16_bf16(pa1, PKV(l1, h1), od, 0, 0, 0);
;     od = __builtin_amdgcn_mfma_f32_32x32x16_bf16(pa2, PKV(l2, h2), od, 0, 0, 0);
;     od = __builtin_amdgcn_mfma_f32_32x32x16_bf16(pa3, PKV(l3, h3), od, 0, 0, 0);
; }
; __device__ __forceinline__ void pv_d0(f32x16* o, int vb, bf16x8 pa0, bf16x8 pa1, bf16x8 pa2, bf16x8 pa3) {
;     pv_one<0>(o[0], vb, pa0, pa1, pa2, pa3); pv_one<1>(o[1], vb, pa0, pa1, pa2, pa3); pv_one<2>(o[2], vb, pa0, pa1, pa2, pa3); pv_one<3>(o[3], vb, pa0, pa1, pa2, pa3);
.Lmb_pv_h1:
	ds_read_b64_tr_b16 v[240:241], v175 offset:0
	ds_read_b64_tr_b16 v[242:243], v175 offset:2048
	ds_read_b64_tr_b16 v[244:245], v175 offset:4096
	ds_read_b64_tr_b16 v[246:247], v175 offset:6144
	ds_read_b64_tr_b16 v[152:153], v175 offset:8192
	ds_read_b64_tr_b16 v[154:155], v175 offset:10240
	ds_read_b64_tr_b16 v[156:157], v175 offset:12288
	ds_read_b64_tr_b16 v[158:159], v175 offset:14336
	s_waitcnt lgkmcnt(0)
	v_mfma_f32_32x32x16_bf16 v[0:15], v[232:235], v[240:243], v[0:15]
	ds_read_b64_tr_b16 v[240:241], v175 offset:512
	ds_read_b64_tr_b16 v[242:243], v175 offset:2560
	v_mfma_f32_32x32x16_bf16 v[0:15], v[236:239], v[244:247], v[0:15]
	ds_read_b64_tr_b16 v[244:245], v175 offset:4608
	ds_read_b64_tr_b16 v[246:247], v175 offset:6656
	v_max3_f32 v254, v80, v81, v82
	v_max3_f32 v255, v83, v84, v85
	v_max3_f32 v254, v254, v86, v87
	v_max3_f32 v255, v255, v88, v89
	v_max3_f32 v254, v254, v90, v91
	v_max3_f32 v255, v255, v92, v93
	v_mfma_f32_32x32x16_bf16 v[0:15], v[144:147], v[152:155], v[0:15]
	ds_read_b64_tr_b16 v[152:153], v175 offset:8704
	ds_read_b64_tr_b16 v[154:155], v175 offset:10752
	v_max3_f32 v254, v254, v94, v95
	v_max3_f32 v255, v255, v64, v65
	v_max3_f32 v254, v254, v66, v67
	v_max3_f32 v255, v255, v68, v69
	v_max3_f32 v254, v254, v70, v71
	v_max3_f32 v255, v255, v72, v73
	v_mfma_f32_32x32x16_bf16 v[0:15], v[148:151], v[156:159], v[0:15]
	ds_read_b64_tr_b16 v[156:157], v175 offset:12800
	ds_read_b64_tr_b16 v[158:159], v175 offset:14848
	v_max3_f32 v254, v254, v74, v75
	v_max3_f32 v255, v255, v76, v77
	v_max3_f32 v254, v254, v78, v79
	v_max_f32_e32 v254, v254, v255
	v_mov_b32_e32 v255, v254
	s_waitcnt lgkmcnt(0)
	v_mfma_f32_32x32x16_bf16 v[48:63], v[232:235], v[240:243], v[48:63]
	ds_read_b64_tr_b16 v[240:241], v175 offset:1024
	ds_read_b64_tr_b16 v[242:243], v175 offset:3072
	v_permlane32_swap_b32_e32 v254, v255
	v_max_f32_e32 v254, v254, v255
	v_cmp_ge_f32_e32 vcc, s35, v254
	v_mfma_f32_32x32x16_bf16 v[48:63], v[236:239], v[244:247], v[48:63]
	ds_read_b64_tr_b16 v[244:245], v175 offset:5120
	ds_read_b64_tr_b16 v[246:247], v175 offset:7168
	v_mfma_f32_32x32x16_bf16 v[48:63], v[144:147], v[152:155], v[48:63]
	ds_read_b64_tr_b16 v[152:153], v175 offset:9216
	ds_read_b64_tr_b16 v[154:155], v175 offset:11264
	v_mfma_f32_32x32x16_bf16 v[48:63], v[148:151], v[156:159], v[48:63]
	ds_read_b64_tr_b16 v[156:157], v175 offset:13312
	ds_read_b64_tr_b16 v[158:159], v175 offset:15360
	s_waitcnt lgkmcnt(0)
	v_mfma_f32_32x32x16_bf16 v[32:47], v[232:235], v[240:243], v[32:47]
	ds_read_b64_tr_b16 v[240:241], v175 offset:1536
	ds_read_b64_tr_b16 v[242:243], v175 offset:3584
	v_mfma_f32_32x32x16_bf16 v[32:47], v[236:239], v[244:247], v[32:47]
	ds_read_b64_tr_b16 v[244:245], v175 offset:5632
	ds_read_b64_tr_b16 v[246:247], v175 offset:7680
	v_mfma_f32_32x32x16_bf16 v[32:47], v[144:147], v[152:155], v[32:47]
	ds_read_b64_tr_b16 v[152:153], v175 offset:9728
	ds_read_b64_tr_b16 v[154:155], v175 offset:11776
	v_mfma_f32_32x32x16_bf16 v[32:47], v[148:151], v[156:159], v[32:47]
	ds_read_b64_tr_b16 v[156:157], v175 offset:13824
	ds_read_b64_tr_b16 v[158:159], v175 offset:15872
	s_waitcnt lgkmcnt(0)
	v_mfma_f32_32x32x16_bf16 v[16:31], v[232:235], v[240:243], v[16:31]
	v_mfma_f32_32x32x16_bf16 v[16:31], v[236:239], v[244:247], v[16:31]
	v_mfma_f32_32x32x16_bf16 v[16:31], v[144:147], v[152:155], v[16:31]
	v_mfma_f32_32x32x16_bf16 v[16:31], v[148:151], v[156:159], v[16:31]
	s_nop 3
	s_cmp_eq_u64 vcc, exec
	s_cselect_b64 s[4:5], -1, 0
	s_cbranch_scc1 .Lmb_cm_h1
	v_max_f32_e32 v255, 0, v254
	v_exp_f32_e64 v251, -v255
	v_add_f32_e32 v250, v250, v255
	v_sub_f32_e32 v80, v80, v255
	v_sub_f32_e32 v81, v81, v255
	v_sub_f32_e32 v82, v82, v255
	v_sub_f32_e32 v83, v83, v255
	v_sub_f32_e32 v84, v84, v255
	v_sub_f32_e32 v85, v85, v255
	v_sub_f32_e32 v86, v86, v255
	v_sub_f32_e32 v87, v87, v255
	v_sub_f32_e32 v88, v88, v255
	v_sub_f32_e32 v89, v89, v255
	v_sub_f32_e32 v90, v90, v255
	v_sub_f32_e32 v91, v91, v255
	v_sub_f32_e32 v92, v92, v255
	v_sub_f32_e32 v93, v93, v255
	v_sub_f32_e32 v94, v94, v255
	v_sub_f32_e32 v95, v95, v255
	v_sub_f32_e32 v64, v64, v255
	v_sub_f32_e32 v65, v65, v255
	v_sub_f32_e32 v66, v66, v255
	v_sub_f32_e32 v67, v67, v255
	v_sub_f32_e32 v68, v68, v255
	v_sub_f32_e32 v69, v69, v255
	v_sub_f32_e32 v70, v70, v255
	v_sub_f32_e32 v71, v71, v255
	v_sub_f32_e32 v72, v72, v255
	v_sub_f32_e32 v73, v73, v255
	v_sub_f32_e32 v74, v74, v255
	v_sub_f32_e32 v75, v75, v255
	v_sub_f32_e32 v76, v76, v255
	v_sub_f32_e32 v77, v77, v255
	v_sub_f32_e32 v78, v78, v255
	v_sub_f32_e32 v79, v79, v255
	s_mov_b32 s29, -1

; __device__ __forceinline__ float half_max(float v) { auto rr = __builtin_amdgcn_permlane32_swap(__float_as_uint(v), __float_as_uint(v), false, false); return fmaxf(__uint_as_float(rr[0]), __uint_as_float(rr[1])); }
; __device__ __forceinline__ void partialSM(f32x16& p0, f32x16& p1, const LAS float* tbp, int relc, float cL, float cR, float& m_reg, float& mn, float& alpha) {
;     float cb = 0.f;
;     if (relc + 63 <= -559) cb = cL;
;     else if (relc - 31 >= 559) cb = cR;
;     else {
; #pragma unroll
;         for (int r = 0; r < 16; ++r) { p0[r] += tbp[(r & 3) + 8 * (r >> 2)]; p1[r] += tbp[32 + (r & 3) + 8 * (r >> 2)]; }
;     }
;     float pmax = p0[0];
; #pragma unroll
;     for (int r = 1; r < 16; ++r) pmax = fmaxf(pmax, p0[r]);
; #pragma unroll
;     for (int r = 0; r < 16; ++r) pmax = fmaxf(pmax, p1[r]);
;     pmax = half_max(pmax) + cb;
;     if (__builtin_expect(__all(pmax - m_reg <= 8.f), 1)) { mn = m_reg; alpha = 1.f; }
;     else { mn = fmaxf(m_reg, pmax); alpha = __builtin_amdgcn_exp2f(m_reg - mn); m_reg = mn; }
;     const float sh = mn - cb;
; #pragma unroll
;     for (int r = 0; r < 16; ++r) { p0[r] -= sh; p1[r] -= sh; }
; #pragma unroll
;     for (int r = 0; r < 16; ++r) p0[r] = __builtin_amdgcn_exp2f(p0[r]);
; }
; __device__ __forceinline__ void finishSM(f32x16& p0, f32x16& p1, float alpha, float& l_reg, bf16x8& pa0, bf16x8& pa1, bf16x8& pa2, bf16x8& pa3) {
; #pragma unroll
;     for (int r = 0; r < 16; ++r) p1[r] = __builtin_amdgcn_exp2f(p1[r]);
.Lmb_w1:
	ds_write_b128 v210, v[120:123]
	ds_write_b128 v211, v[124:127]
	ds_write_b128 v212, v[112:115] offset:49152
	ds_write_b128 v213, v[116:119] offset:49152
	s_and_b64 vcc, exec, s[4:5]
	s_cbranch_vccnz .Lmb_nr_h1
	s_and_saveexec_b64 vcc, s[0:1]
	ds_write_b32 v215, v251 offset:128
	s_or_b64 exec, exec, vcc
	s_waitcnt lgkmcnt(0)
	ds_read_b128 v[112:115], v179 offset:224
	ds_read_b128 v[116:119], v179 offset:192
	ds_read_b128 v[120:123], v179 offset:160
	ds_read_b128 v[124:127], v179 offset:128
	s_waitcnt lgkmcnt(0)
	s_nop 3
	v_pk_mul_f32 v[14:15], v[14:15], v[114:115]
	v_pk_mul_f32 v[12:13], v[12:13], v[112:113]
	v_pk_mul_f32 v[10:11], v[10:11], v[118:119]
	v_pk_mul_f32 v[8:9], v[8:9], v[116:117]
	v_pk_mul_f32 v[6:7], v[6:7], v[122:123]
	v_pk_mul_f32 v[4:5], v[4:5], v[120:121]
	v_pk_mul_f32 v[2:3], v[2:3], v[126:127]
	v_pk_mul_f32 v[0:1], v[0:1], v[124:125]
	v_pk_mul_f32 v[62:63], v[62:63], v[114:115]
	v_pk_mul_f32 v[60:61], v[60:61], v[112:113]
	v_pk_mul_f32 v[58:59], v[58:59], v[118:119]
	v_pk_mul_f32 v[56:57], v[56:57], v[116:117]
	v_pk_mul_f32 v[54:55], v[54:55], v[122:123]
	v_pk_mul_f32 v[52:53], v[52:53], v[120:121]
	v_pk_mul_f32 v[50:51], v[50:51], v[126:127]
	v_pk_mul_f32 v[48:49], v[48:49], v[124:125]
	v_pk_mul_f32 v[46:47], v[46:47], v[114:115]
	v_pk_mul_f32 v[44:45], v[44:45], v[112:113]
	v_pk_mul_f32 v[42:43], v[42:43], v[118:119]
	v_pk_mul_f32 v[40:41], v[40:41], v[116:117]
	v_pk_mul_f32 v[38:39], v[38:39], v[122:123]
	v_pk_mul_f32 v[36:37], v[36:37], v[120:121]
	v_pk_mul_f32 v[34:35], v[34:35], v[126:127]
	v_pk_mul_f32 v[32:33], v[32:33], v[124:125]
	v_pk_mul_f32 v[30:31], v[30:31], v[114:115]
	v_pk_mul_f32 v[28:29], v[28:29], v[112:113]
	v_pk_mul_f32 v[26:27], v[26:27], v[118:119]
	v_pk_mul_f32 v[24:25], v[24:25], v[116:117]
	v_pk_mul_f32 v[22:23], v[22:23], v[122:123]
	v_pk_mul_f32 v[20:21], v[20:21], v[120:121]
	v_pk_mul_f32 v[18:19], v[18:19], v[126:127]
	v_pk_mul_f32 v[16:17], v[16:17], v[124:125]
.Lmb_nr_h1:
	v_exp_f32_e32 v80, v80
	v_exp_f32_e32 v81, v81
	v_exp_f32_e32 v82, v82
	v_exp_f32_e32 v83, v83
	v_exp_f32_e32 v84, v84
	v_exp_f32_e32 v85, v85
	v_exp_f32_e32 v86, v86
	v_exp_f32_e32 v87, v87
	v_exp_f32_e32 v88, v88
	v_exp_f32_e32 v89, v89
	v_exp_f32_e32 v90, v90
	v_exp_f32_e32 v91, v91
	v_exp_f32_e32 v92, v92
	v_exp_f32_e32 v93, v93
	v_exp_f32_e32 v94, v94
	v_exp_f32_e32 v95, v95
	v_exp_f32_e32 v64, v64
	v_exp_f32_e32 v65, v65
	v_exp_f32_e32 v66, v66
	v_exp_f32_e32 v67, v67
	v_exp_f32_e32 v68, v68
	v_exp_f32_e32 v69, v69
	v_exp_f32_e32 v70, v70
	v_exp_f32_e32 v71, v71
	v_exp_f32_e32 v72, v72
	v_exp_f32_e32 v73, v73
	v_exp_f32_e32 v74, v74
	v_exp_f32_e32 v75, v75
	v_exp_f32_e32 v76, v76
	v_exp_f32_e32 v77, v77
	v_exp_f32_e32 v78, v78
	v_exp_f32_e32 v79, v79
	s_addk_i32 s6, 0x40
	s_mov_b32 s28, 0
	s_cmpk_lt_i32 s6, 0xfd93
	s_cbranch_scc1 .Lmb_cls_h2
	s_mov_b32 s28, 2
	s_cmpk_gt_i32 s6, 0x24d
	s_cbranch_scc1 .Lmb_cls_h2
	s_mov_b32 s28, 1

; #define LAS __attribute__((address_space(3)))
; __device__ __forceinline__ float half_add(float v) { auto rr = __builtin_amdgcn_permlane32_swap(__float_as_uint(v), __float_as_uint(v), false, false); return __uint_as_float(rr[0]) + __uint_as_float(rr[1]); }
; __device__ __forceinline__ void finishSM(f32x16& p0, f32x16& p1, float alpha, float& l_reg, bf16x8& pa0, bf16x8& pa1, bf16x8& pa2, bf16x8& pa3) {
; #pragma unroll
;     for (int r = 0; r < 16; ++r) p1[r] = __builtin_amdgcn_exp2f(p1[r]);
;     float ps = 0;
; #pragma unroll
;     for (int r = 0; r < 16; ++r) ps += p0[r];
; #pragma unroll
;     for (int r = 0; r < 16; ++r) ps += p1[r];
;     ps = half_add(ps);
;     l_reg = l_reg * alpha + ps;
;     PK4(p0, 0, pa0); PK4(p0, 8, pa1); PK4(p1, 0, pa2); PK4(p1, 8, pa3);
; }
; __device__ __forceinline__ void qkt(f32x16& p0, f32x16& p1, const LAS unsigned char* Ks, const bf16x8* qr, int r32, int cb0) {
; #pragma unroll
;     for (int i = 0; i < 16; ++i) { p0[i] = 0.f; p1[i] = 0.f; }
; #pragma unroll
;     for (int d0 = 0; d0 < 4; ++d0) { const int cb = cb0 + d0 * 32;
;         const bf16x8 b0 = *(const LAS bf16x8*)(Ks + KSWZ(r32, cb));
;         const bf16x8 b1 = *(const LAS bf16x8*)(Ks + KSWZ(32 + r32, cb));
;         p0 = __builtin_amdgcn_mfma_f32_32x32x16_bf16(b0, qr[d0], p0, 0, 0, 0);
;         p1 = __builtin_amdgcn_mfma_f32_32x32x16_bf16(b1, qr[d0], p1, 0, 0, 0); }
; }
.Lmb_nrf_h2:
	ds_read_b128 v[144:147], v219 offset:32768
	ds_read_b128 v[120:123], v224
	ds_read_b128 v[148:151], v219 offset:40960
	ds_read_b128 v[112:115], v220 offset:32768
	ds_read_b128 v[116:119], v220 offset:40960
	ds_read_b128 v[124:127], v224 offset:1024
	v_add_f32_e32 v254, v80, v81
	v_add_f32_e32 v255, v82, v83
	v_add_f32_e32 v254, v254, v84
	v_add_f32_e32 v255, v255, v85
	v_add_f32_e32 v254, v254, v86
	v_add_f32_e32 v255, v255, v87
	v_add_f32_e32 v254, v254, v88
	v_add_f32_e32 v255, v255, v89
	v_add_f32_e32 v254, v254, v90
	v_add_f32_e32 v255, v255, v91
	v_add_f32_e32 v254, v254, v92
	v_add_f32_e32 v255, v255, v93
	v_add_f32_e32 v254, v254, v94
	v_add_f32_e32 v255, v255, v95
	v_add_f32_e32 v254, v254, v64
	v_add_f32_e32 v255, v255, v65
	v_add_f32_e32 v254, v254, v66
	v_add_f32_e32 v255, v255, v67
	v_add_f32_e32 v254, v254, v68
	v_add_f32_e32 v255, v255, v69
	v_add_f32_e32 v254, v254, v70
	v_add_f32_e32 v255, v255, v71
	v_add_f32_e32 v254, v254, v72
	v_add_f32_e32 v255, v255, v73
	v_add_f32_e32 v254, v254, v74
	v_add_f32_e32 v255, v255, v75
	v_add_f32_e32 v254, v254, v76
	v_add_f32_e32 v255, v255, v77
	v_add_f32_e32 v254, v254, v78
	v_add_f32_e32 v255, v255, v79
	v_add_f32_e32 v254, v254, v255
	v_mov_b32_e32 v255, v254
	s_waitcnt lgkmcnt(4)
	v_mfma_f32_32x32x16_bf16 v[232:247], v[144:147], v[120:123], v[96:111]
	v_permlane32_swap_b32_e32 v254, v255
	v_cvt_pk_bf16_f32 v80, v80, v81
	v_cvt_pk_bf16_f32 v81, v82, v83
	v_cvt_pk_bf16_f32 v82, v84, v85
	v_add_f32_e32 v254, v254, v255
	v_fma_f32 v216, v216, v251, v254
	s_waitcnt lgkmcnt(3)
	v_mfma_f32_32x32x16_bf16 v[144:159], v[148:151], v[120:123], v[96:111]
	ds_read_b128 v[120:123], v224 offset:2048
	s_and_b64 vcc, exec, s[4:5]
	s_cbranch_vccnz .Lmb_a1_h2
	v_mov_b32_e32 v251, 1.0
.Lmb_a1_h2:
	v_cvt_pk_bf16_f32 v83, v86, v87
	v_cvt_pk_bf16_f32 v84, v88, v89
	v_cvt_pk_bf16_f32 v85, v90, v91
	v_cvt_pk_bf16_f32 v86, v92, v93
	v_cvt_pk_bf16_f32 v87, v94, v95
	v_cvt_pk_bf16_f32 v64, v64, v65
	s_waitcnt lgkmcnt(1)
	v_mfma_f32_32x32x16_bf16 v[232:247], v[112:115], v[124:127], v[232:247]
	v_cvt_pk_bf16_f32 v65, v66, v67
	v_cvt_pk_bf16_f32 v66, v68, v69
	v_cvt_pk_bf16_f32 v67, v70, v71
	v_cvt_pk_bf16_f32 v68, v72, v73
	v_cvt_pk_bf16_f32 v69, v74, v75
	v_cvt_pk_bf16_f32 v70, v76, v77
	v_mfma_f32_32x32x16_bf16 v[144:159], v[116:119], v[124:127], v[144:159]
	ds_read_b128 v[112:115], v221 offset:32768
	ds_read_b128 v[116:119], v221 offset:40960
	ds_read_b128 v[124:127], v224 offset:3072
	v_cvt_pk_bf16_f32 v71, v78, v79
	ds_read_b128 v[88:91], v222 offset:32768
	ds_read_b128 v[92:95], v222 offset:40960
	s_waitcnt lgkmcnt(4)
	v_mfma_f32_32x32x16_bf16 v[232:247], v[112:115], v[120:123], v[232:247]
	v_permlane32_swap_b32_e32 v80, v82
	v_permlane32_swap_b32_e32 v81, v83
	v_permlane32_swap_b32_e32 v84, v86
	v_permlane32_swap_b32_e32 v85, v87
	s_waitcnt lgkmcnt(3)
	v_mfma_f32_32x32x16_bf16 v[144:159], v[116:119], v[120:123], v[144:159]
	v_permlane32_swap_b32_e32 v64, v66
	v_permlane32_swap_b32_e32 v65, v67
	v_permlane32_swap_b32_e32 v68, v70
	v_permlane32_swap_b32_e32 v69, v71
	s_waitcnt lgkmcnt(1)
	v_mfma_f32_32x32x16_bf16 v[232:247], v[88:91], v[124:127], v[232:247]
	s_waitcnt lgkmcnt(0)
	v_mfma_f32_32x32x16_bf16 v[144:159], v[92:95], v[124:127], v[144:159]
	s_and_b64 vcc, exec, s[26:27]
	s_cbranch_vccnz .Lmb_skipld
	s_mov_b32 s4, 0xfffa0000
	s_mov_b32 s5, -1
	v_lshl_add_u64 v[120:121], v[182:183], 0, s[4:5]
	global_load_dwordx4 v[120:123], v[120:121], off
	global_load_dwordx4 v[124:127], v[182:183], off
	s_mov_b64 s[4:5], 0x60000
	v_lshl_add_u64 v[112:113], v[182:183], 0, s[4:5]
	global_load_dwordx4 v[112:115], v[112:113], off offset:-2048
	s_mov_b64 s[4:5], 0xc0000
	v_lshl_add_u64 v[116:117], v[182:183], 0, s[4:5]
	global_load_dwordx4 v[116:119], v[116:117], off offset:-2048

; #define LAS __attribute__((address_space(3)))
; __device__ __forceinline__ void partialSM(f32x16& p0, f32x16& p1, const LAS float* tbp, int relc, float cL, float cR, float& m_reg, float& mn, float& alpha) {
;     float cb = 0.f;
;     if (relc + 63 <= -559) cb = cL;
;     else if (relc - 31 >= 559) cb = cR;
;     else {
; #pragma unroll
;         for (int r = 0; r < 16; ++r) { p0[r] += tbp[(r & 3) + 8 * (r >> 2)]; p1[r] += tbp[32 + (r & 3) + 8 * (r >> 2)]; }
;     }
;     float pmax = p0[0];
; #pragma unroll
;     for (int r = 1; r < 16; ++r) pmax = fmaxf(pmax, p0[r]);
; #pragma unroll
;     for (int r = 0; r < 16; ++r) pmax = fmaxf(pmax, p1[r]);
;     pmax = half_max(pmax) + cb;
;     if (__builtin_expect(__all(pmax - m_reg <= 8.f), 1)) { mn = m_reg; alpha = 1.f; }
;     else { mn = fmaxf(m_reg, pmax); alpha = __builtin_amdgcn_exp2f(m_reg - mn); m_reg = mn; }
;     const float sh = mn - cb;
; #pragma unroll
;     for (int r = 0; r < 16; ++r) { p0[r] -= sh; p1[r] -= sh; }
; #pragma unroll
;     for (int r = 0; r < 16; ++r) p0[r] = __builtin_amdgcn_exp2f(p0[r]);
; }
; template <int D0> __device__ __forceinline__ void pv_one(f32x16& od, int vb, bf16x8 pa0, bf16x8 pa1, bf16x8 pa2, bf16x8 pa3) {
;     s16x4 l0 = tr_read<v_rd_off(D0, 0, 0)>(vb), h0 = tr_read<v_rd_off(D0, 0, 1)>(vb), l1 = tr_read<v_rd_off(D0, 1, 0)>(vb), h1 = tr_read<v_rd_off(D0, 1, 1)>(vb);
;     s16x4 l2 = tr_read<v_rd_off(D0, 2, 0)>(vb), h2 = tr_read<v_rd_off(D0, 2, 1)>(vb), l3 = tr_read<v_rd_off(D0, 3, 0)>(vb), h3 = tr_read<v_rd_off(D0, 3, 1)>(vb);
;     asm volatile("s_waitcnt lgkmcnt(0)" : "+v"(l0), "+v"(h0), "+v"(l1), "+v"(h1), "+v"(l2), "+v"(h2), "+v"(l3), "+v"(h3) :: "memory");
;     od = __builtin_amdgcn_mfma_f32_32x32x16_bf16(pa0, PKV(l0, h0), od, 0, 0, 0);
;     od = __builtin_amdgcn_mfma_f32_32x32x16_bf16(pa1, PKV(l1, h1), od, 0, 0, 0);
;     od = __builtin_amdgcn_mfma_f32_32x32x16_bf16(pa2, PKV(l2, h2), od, 0, 0, 0);
;     od = __builtin_amdgcn_mfma_f32_32x32x16_bf16(pa3, PKV(l3, h3), od, 0, 0, 0);
; }
; __device__ __forceinline__ void pv_d0(f32x16* o, int vb, bf16x8 pa0, bf16x8 pa1, bf16x8 pa2, bf16x8 pa3) {
;     pv_one<0>(o[0], vb, pa0, pa1, pa2, pa3); pv_one<1>(o[1], vb, pa0, pa1, pa2, pa3); pv_one<2>(o[2], vb, pa0, pa1, pa2, pa3); pv_one<3>(o[3], vb, pa0, pa1, pa2, pa3);
.Lmb_pv_h2:
	ds_read_b64_tr_b16 v[88:89], v186 offset:0
	ds_read_b64_tr_b16 v[90:91], v186 offset:2048
	ds_read_b64_tr_b16 v[92:93], v186 offset:4096
	ds_read_b64_tr_b16 v[94:95], v186 offset:6144
	ds_read_b64_tr_b16 v[72:73], v186 offset:8192
	ds_read_b64_tr_b16 v[74:75], v186 offset:10240
	ds_read_b64_tr_b16 v[76:77], v186 offset:12288
	ds_read_b64_tr_b16 v[78:79], v186 offset:14336
	s_waitcnt lgkmcnt(0)
	v_mfma_f32_32x32x16_bf16 v[0:15], v[80:83], v[88:91], v[0:15]
	ds_read_b64_tr_b16 v[88:89], v186 offset:512
	ds_read_b64_tr_b16 v[90:91], v186 offset:2560
	v_mfma_f32_32x32x16_bf16 v[0:15], v[84:87], v[92:95], v[0:15]
	ds_read_b64_tr_b16 v[92:93], v186 offset:4608
	ds_read_b64_tr_b16 v[94:95], v186 offset:6656
	v_max3_f32 v254, v232, v233, v234
	v_max3_f32 v255, v235, v236, v237
	v_max3_f32 v254, v254, v238, v239
	v_max3_f32 v255, v255, v240, v241
	v_max3_f32 v254, v254, v242, v243
	v_max3_f32 v255, v255, v244, v245
	v_mfma_f32_32x32x16_bf16 v[0:15], v[64:67], v[72:75], v[0:15]
	ds_read_b64_tr_b16 v[72:73], v186 offset:8704
	ds_read_b64_tr_b16 v[74:75], v186 offset:10752
	v_max3_f32 v254, v254, v246, v247
	v_max3_f32 v255, v255, v144, v145
	v_max3_f32 v254, v254, v146, v147
	v_max3_f32 v255, v255, v148, v149
	v_max3_f32 v254, v254, v150, v151
	v_max3_f32 v255, v255, v152, v153
	v_mfma_f32_32x32x16_bf16 v[0:15], v[68:71], v[76:79], v[0:15]
	ds_read_b64_tr_b16 v[76:77], v186 offset:12800
	ds_read_b64_tr_b16 v[78:79], v186 offset:14848
	v_max3_f32 v254, v254, v154, v155
	v_max3_f32 v255, v255, v156, v157
	v_max3_f32 v254, v254, v158, v159
	v_max_f32_e32 v254, v254, v255
	v_mov_b32_e32 v255, v254
	s_waitcnt lgkmcnt(0)
	v_mfma_f32_32x32x16_bf16 v[48:63], v[80:83], v[88:91], v[48:63]
	ds_read_b64_tr_b16 v[88:89], v186 offset:1024
	ds_read_b64_tr_b16 v[90:91], v186 offset:3072
	v_permlane32_swap_b32_e32 v254, v255
	v_max_f32_e32 v254, v254, v255
	v_cmp_ge_f32_e32 vcc, s35, v254
	v_mfma_f32_32x32x16_bf16 v[48:63], v[84:87], v[92:95], v[48:63]
	ds_read_b64_tr_b16 v[92:93], v186 offset:5120
	ds_read_b64_tr_b16 v[94:95], v186 offset:7168
	v_mfma_f32_32x32x16_bf16 v[48:63], v[64:67], v[72:75], v[48:63]
	ds_read_b64_tr_b16 v[72:73], v186 offset:9216
	ds_read_b64_tr_b16 v[74:75], v186 offset:11264
	v_mfma_f32_32x32x16_bf16 v[48:63], v[68:71], v[76:79], v[48:63]
	ds_read_b64_tr_b16 v[76:77], v186 offset:13312
	ds_read_b64_tr_b16 v[78:79], v186 offset:15360
	s_waitcnt lgkmcnt(0)
	v_mfma_f32_32x32x16_bf16 v[32:47], v[80:83], v[88:91], v[32:47]
	ds_read_b64_tr_b16 v[88:89], v186 offset:1536
	ds_read_b64_tr_b16 v[90:91], v186 offset:3584
	v_mfma_f32_32x32x16_bf16 v[32:47], v[84:87], v[92:95], v[32:47]
	ds_read_b64_tr_b16 v[92:93], v186 offset:5632
	ds_read_b64_tr_b16 v[94:95], v186 offset:7680
	v_mfma_f32_32x32x16_bf16 v[32:47], v[64:67], v[72:75], v[32:47]
	ds_read_b64_tr_b16 v[72:73], v186 offset:9728
	ds_read_b64_tr_b16 v[74:75], v186 offset:11776
	v_mfma_f32_32x32x16_bf16 v[32:47], v[68:71], v[76:79], v[32:47]
	ds_read_b64_tr_b16 v[76:77], v186 offset:13824
	ds_read_b64_tr_b16 v[78:79], v186 offset:15872
	s_waitcnt lgkmcnt(0)
	v_mfma_f32_32x32x16_bf16 v[16:31], v[80:83], v[88:91], v[16:31]
	v_mfma_f32_32x32x16_bf16 v[16:31], v[84:87], v[92:95], v[16:31]
	v_mfma_f32_32x32x16_bf16 v[16:31], v[64:67], v[72:75], v[16:31]
	v_mfma_f32_32x32x16_bf16 v[16:31], v[68:71], v[76:79], v[16:31]
	s_nop 3
	s_cmp_eq_u64 vcc, exec
	s_cselect_b64 s[4:5], -1, 0
	s_cbranch_scc1 .Lmb_cm_h2
	v_max_f32_e32 v255, 0, v254
	v_exp_f32_e64 v251, -v255
	v_add_f32_e32 v250, v250, v255
	v_sub_f32_e32 v232, v232, v255
	v_sub_f32_e32 v233, v233, v255
	v_sub_f32_e32 v234, v234, v255
	v_sub_f32_e32 v235, v235, v255
	v_sub_f32_e32 v236, v236, v255
	v_sub_f32_e32 v237, v237, v255
	v_sub_f32_e32 v238, v238, v255
	v_sub_f32_e32 v239, v239, v255
	v_sub_f32_e32 v240, v240, v255
	v_sub_f32_e32 v241, v241, v255
	v_sub_f32_e32 v242, v242, v255
	v_sub_f32_e32 v243, v243, v255
	v_sub_f32_e32 v244, v244, v255
	v_sub_f32_e32 v245, v245, v255
	v_sub_f32_e32 v246, v246, v255
	v_sub_f32_e32 v247, v247, v255
	v_sub_f32_e32 v144, v144, v255
	v_sub_f32_e32 v145, v145, v255
	v_sub_f32_e32 v146, v146, v255
	v_sub_f32_e32 v147, v147, v255
	v_sub_f32_e32 v148, v148, v255
	v_sub_f32_e32 v149, v149, v255
	v_sub_f32_e32 v150, v150, v255
	v_sub_f32_e32 v151, v151, v255
	v_sub_f32_e32 v152, v152, v255
	v_sub_f32_e32 v153, v153, v255
	v_sub_f32_e32 v154, v154, v255
	v_sub_f32_e32 v155, v155, v255
	v_sub_f32_e32 v156, v156, v255
	v_sub_f32_e32 v157, v157, v255
	v_sub_f32_e32 v158, v158, v255
	v_sub_f32_e32 v159, v159, v255
	s_mov_b32 s29, -1

; __device__ __forceinline__ float half_max(float v) { auto rr = __builtin_amdgcn_permlane32_swap(__float_as_uint(v), __float_as_uint(v), false, false); return fmaxf(__uint_as_float(rr[0]), __uint_as_float(rr[1])); }
; __device__ __forceinline__ void partialSM(f32x16& p0, f32x16& p1, const LAS float* tbp, int relc, float cL, float cR, float& m_reg, float& mn, float& alpha) {
;     float cb = 0.f;
;     if (relc + 63 <= -559) cb = cL;
;     else if (relc - 31 >= 559) cb = cR;
;     else {
; #pragma unroll
;         for (int r = 0; r < 16; ++r) { p0[r] += tbp[(r & 3) + 8 * (r >> 2)]; p1[r] += tbp[32 + (r & 3) + 8 * (r >> 2)]; }
;     }
;     float pmax = p0[0];
; #pragma unroll
;     for (int r = 1; r < 16; ++r) pmax = fmaxf(pmax, p0[r]);
; #pragma unroll
;     for (int r = 0; r < 16; ++r) pmax = fmaxf(pmax, p1[r]);
;     pmax = half_max(pmax) + cb;
;     if (__builtin_expect(__all(pmax - m_reg <= 8.f), 1)) { mn = m_reg; alpha = 1.f; }
;     else { mn = fmaxf(m_reg, pmax); alpha = __builtin_amdgcn_exp2f(m_reg - mn); m_reg = mn; }
;     const float sh = mn - cb;
; #pragma unroll
;     for (int r = 0; r < 16; ++r) { p0[r] -= sh; p1[r] -= sh; }
; #pragma unroll
;     for (int r = 0; r < 16; ++r) p0[r] = __builtin_amdgcn_exp2f(p0[r]);
; }
; __device__ __forceinline__ void finishSM(f32x16& p0, f32x16& p1, float alpha, float& l_reg, bf16x8& pa0, bf16x8& pa1, bf16x8& pa2, bf16x8& pa3) {
; #pragma unroll
;     for (int r = 0; r < 16; ++r) p1[r] = __builtin_amdgcn_exp2f(p1[r]);
.Lmb_w2:
	ds_write_b128 v210, v[128:131] offset:16384
	ds_write_b128 v211, v[140:143] offset:16384
	ds_write_b128 v212, v[132:135] offset:32768
	ds_write_b128 v213, v[136:139] offset:32768
	s_and_b64 vcc, exec, s[4:5]
	s_cbranch_vccnz .Lmb_nr_h2
	s_and_saveexec_b64 vcc, s[0:1]
	ds_write_b32 v215, v251 offset:128
	s_or_b64 exec, exec, vcc
	s_waitcnt lgkmcnt(0)
	ds_read_b128 v[128:131], v179 offset:224
	ds_read_b128 v[132:135], v179 offset:192
	ds_read_b128 v[136:139], v179 offset:160
	ds_read_b128 v[140:143], v179 offset:128
	s_waitcnt lgkmcnt(0)
	s_nop 3
	v_pk_mul_f32 v[14:15], v[14:15], v[130:131]
	v_pk_mul_f32 v[12:13], v[12:13], v[128:129]
	v_pk_mul_f32 v[10:11], v[10:11], v[134:135]
	v_pk_mul_f32 v[8:9], v[8:9], v[132:133]
	v_pk_mul_f32 v[6:7], v[6:7], v[138:139]
	v_pk_mul_f32 v[4:5], v[4:5], v[136:137]
	v_pk_mul_f32 v[2:3], v[2:3], v[142:143]
	v_pk_mul_f32 v[0:1], v[0:1], v[140:141]
	v_pk_mul_f32 v[62:63], v[62:63], v[130:131]
	v_pk_mul_f32 v[60:61], v[60:61], v[128:129]
	v_pk_mul_f32 v[58:59], v[58:59], v[134:135]
	v_pk_mul_f32 v[56:57], v[56:57], v[132:133]
	v_pk_mul_f32 v[54:55], v[54:55], v[138:139]
	v_pk_mul_f32 v[52:53], v[52:53], v[136:137]
	v_pk_mul_f32 v[50:51], v[50:51], v[142:143]
	v_pk_mul_f32 v[48:49], v[48:49], v[140:141]
	v_pk_mul_f32 v[46:47], v[46:47], v[130:131]
	v_pk_mul_f32 v[44:45], v[44:45], v[128:129]
	v_pk_mul_f32 v[42:43], v[42:43], v[134:135]
	v_pk_mul_f32 v[40:41], v[40:41], v[132:133]
	v_pk_mul_f32 v[38:39], v[38:39], v[138:139]
	v_pk_mul_f32 v[36:37], v[36:37], v[136:137]
	v_pk_mul_f32 v[34:35], v[34:35], v[142:143]
	v_pk_mul_f32 v[32:33], v[32:33], v[140:141]
	v_pk_mul_f32 v[30:31], v[30:31], v[130:131]
	v_pk_mul_f32 v[28:29], v[28:29], v[128:129]
	v_pk_mul_f32 v[26:27], v[26:27], v[134:135]
	v_pk_mul_f32 v[24:25], v[24:25], v[132:133]
	v_pk_mul_f32 v[22:23], v[22:23], v[138:139]
	v_pk_mul_f32 v[20:21], v[20:21], v[136:137]
	v_pk_mul_f32 v[18:19], v[18:19], v[142:143]
	v_pk_mul_f32 v[16:17], v[16:17], v[140:141]
.Lmb_nr_h2:
	v_exp_f32_e32 v232, v232
	v_exp_f32_e32 v233, v233
	v_exp_f32_e32 v234, v234
	v_exp_f32_e32 v235, v235
	v_exp_f32_e32 v236, v236
	v_exp_f32_e32 v237, v237
	v_exp_f32_e32 v238, v238
	v_exp_f32_e32 v239, v239
	v_exp_f32_e32 v240, v240
	v_exp_f32_e32 v241, v241
	v_exp_f32_e32 v242, v242
	v_exp_f32_e32 v243, v243
	v_exp_f32_e32 v244, v244
	v_exp_f32_e32 v245, v245
	v_exp_f32_e32 v246, v246
	v_exp_f32_e32 v247, v247
	v_exp_f32_e32 v144, v144
	v_exp_f32_e32 v145, v145
	v_exp_f32_e32 v146, v146
	v_exp_f32_e32 v147, v147
	v_exp_f32_e32 v148, v148
	v_exp_f32_e32 v149, v149
	v_exp_f32_e32 v150, v150
	v_exp_f32_e32 v151, v151
	v_exp_f32_e32 v152, v152
	v_exp_f32_e32 v153, v153
	v_exp_f32_e32 v154, v154
	v_exp_f32_e32 v155, v155
	v_exp_f32_e32 v156, v156
	v_exp_f32_e32 v157, v157
	v_exp_f32_e32 v158, v158
	v_exp_f32_e32 v159, v159
	s_addk_i32 s6, 0x40
	v_add_co_u32_e32 v182, vcc, 0x180000, v182
	s_nop 1
	v_addc_co_u32_e32 v183, vcc, 0, v183, vcc
	v_add_u32_e32 v223, 0x200, v223
	s_and_b64 vcc, exec, s[26:27]
	s_cbranch_vccz .Lmb_loop
	s_mov_b32 s28, 0
	s_cmpk_lt_i32 s6, 0xfd93
	s_cbranch_scc1 .Lmb_cls_pe
	s_mov_b32 s28, 2
	s_cmpk_gt_i32 s6, 0x24d
	s_cbranch_scc1 .Lmb_cls_pe
	s_mov_b32 s28, 1

; #define LAS __attribute__((address_space(3)))
; __device__ __forceinline__ void partialSM(f32x16& p0, f32x16& p1, const LAS float* tbp, int relc, float cL, float cR, float& m_reg, float& mn, float& alpha) {
;     float cb = 0.f;
;     if (relc + 63 <= -559) cb = cL;
;     else if (relc - 31 >= 559) cb = cR;
;     else {
; #pragma unroll
;         for (int r = 0; r < 16; ++r) { p0[r] += tbp[(r & 3) + 8 * (r >> 2)]; p1[r] += tbp[32 + (r & 3) + 8 * (r >> 2)]; }
;     }
;     float pmax = p0[0];
; #pragma unroll
;     for (int r = 1; r < 16; ++r) pmax = fmaxf(pmax, p0[r]);
; #pragma unroll
;     for (int r = 0; r < 16; ++r) pmax = fmaxf(pmax, p1[r]);
;     pmax = half_max(pmax) + cb;
;     if (__builtin_expect(__all(pmax - m_reg <= 8.f), 1)) { mn = m_reg; alpha = 1.f; }
;     else { mn = fmaxf(m_reg, pmax); alpha = __builtin_amdgcn_exp2f(m_reg - mn); m_reg = mn; }
;     const float sh = mn - cb;
; #pragma unroll
;     for (int r = 0; r < 16; ++r) { p0[r] -= sh; p1[r] -= sh; }
; #pragma unroll
;     for (int r = 0; r < 16; ++r) p0[r] = __builtin_amdgcn_exp2f(p0[r]);
; }
; __device__ __forceinline__ void finishSM(f32x16& p0, f32x16& p1, float alpha, float& l_reg, bf16x8& pa0, bf16x8& pa1, bf16x8& pa2, bf16x8& pa3) {
; #pragma unroll
;     for (int r = 0; r < 16; ++r) p1[r] = __builtin_amdgcn_exp2f(p1[r]);
;     float ps = 0;
; #pragma unroll
;     for (int r = 0; r < 16; ++r) ps += p0[r];
; #pragma unroll
;     for (int r = 0; r < 16; ++r) ps += p1[r];
;     ps = half_add(ps);
;     l_reg = l_reg * alpha + ps;
;     PK4(p0, 0, pa0); PK4(p0, 8, pa1); PK4(p1, 0, pa2); PK4(p1, 8, pa3);
; }
; __device__ __forceinline__ void qkt(f32x16& p0, f32x16& p1, const LAS unsigned char* Ks, const bf16x8* qr, int r32, int cb0) {
; #pragma unroll
;     for (int i = 0; i < 16; ++i) { p0[i] = 0.f; p1[i] = 0.f; }
; #pragma unroll
;     for (int d0 = 0; d0 < 4; ++d0) { const int cb = cb0 + d0 * 32;
;         const bf16x8 b0 = *(const LAS bf16x8*)(Ks + KSWZ(r32, cb));
;         const bf16x8 b1 = *(const LAS bf16x8*)(Ks + KSWZ(32 + r32, cb));
;         p0 = __builtin_amdgcn_mfma_f32_32x32x16_bf16(b0, qr[d0], p0, 0, 0, 0);
;         p1 = __builtin_amdgcn_mfma_f32_32x32x16_bf16(b1, qr[d0], p1, 0, 0, 0); }
; }
; template <int D0> __device__ __forceinline__ void pv_one(f32x16& od, int vb, bf16x8 pa0, bf16x8 pa1, bf16x8 pa2, bf16x8 pa3) {
.Lmb_a1_pe:
	v_cvt_pk_bf16_f32 v235, v238, v239
	v_cvt_pk_bf16_f32 v236, v240, v241
	v_cvt_pk_bf16_f32 v237, v242, v243
	v_cvt_pk_bf16_f32 v238, v244, v245
	v_cvt_pk_bf16_f32 v239, v246, v247
	v_cvt_pk_bf16_f32 v144, v144, v145
	s_waitcnt lgkmcnt(1)
	v_mfma_f32_32x32x16_bf16 v[80:95], v[128:131], v[140:143], v[80:95]
	v_cvt_pk_bf16_f32 v145, v146, v147
	v_cvt_pk_bf16_f32 v146, v148, v149
	v_cvt_pk_bf16_f32 v147, v150, v151
	v_cvt_pk_bf16_f32 v148, v152, v153
	v_cvt_pk_bf16_f32 v149, v154, v155
	v_cvt_pk_bf16_f32 v150, v156, v157
	v_mfma_f32_32x32x16_bf16 v[64:79], v[132:135], v[140:143], v[64:79]
	ds_read_b128 v[128:131], v221 offset:49152
	ds_read_b128 v[132:135], v221 offset:57344
	ds_read_b128 v[140:143], v224 offset:3072
	v_cvt_pk_bf16_f32 v151, v158, v159
	ds_read_b128 v[240:243], v222 offset:49152
	ds_read_b128 v[244:247], v222 offset:57344
	s_waitcnt lgkmcnt(4)
	v_mfma_f32_32x32x16_bf16 v[80:95], v[128:131], v[136:139], v[80:95]
	v_permlane32_swap_b32_e32 v232, v234
	v_permlane32_swap_b32_e32 v233, v235
	v_permlane32_swap_b32_e32 v236, v238
	v_permlane32_swap_b32_e32 v237, v239
	s_waitcnt lgkmcnt(3)
	v_mfma_f32_32x32x16_bf16 v[64:79], v[132:135], v[136:139], v[64:79]
	v_permlane32_swap_b32_e32 v144, v146
	v_permlane32_swap_b32_e32 v145, v147
	v_permlane32_swap_b32_e32 v148, v150
	v_permlane32_swap_b32_e32 v149, v151
	s_waitcnt lgkmcnt(1)
	v_mfma_f32_32x32x16_bf16 v[80:95], v[240:243], v[140:143], v[80:95]
	s_waitcnt lgkmcnt(0)
	v_mfma_f32_32x32x16_bf16 v[64:79], v[244:247], v[140:143], v[64:79]
	s_cmp_eq_u32 s28, 1
	s_cbranch_scc0 .Lmb_pv_pe
	ds_read2_b32 v[240:241], v223 offset1:1
	ds_read2_b32 v[242:243], v223 offset0:2 offset1:3
	ds_read2_b32 v[244:245], v223 offset0:8 offset1:9
	ds_read2_b32 v[246:247], v223 offset0:10 offset1:11
	ds_read2_b32 v[152:153], v223 offset0:16 offset1:17
	ds_read2_b32 v[154:155], v223 offset0:18 offset1:19
	ds_read2_b32 v[156:157], v223 offset0:24 offset1:25
	ds_read2_b32 v[158:159], v223 offset0:26 offset1:27
	s_waitcnt lgkmcnt(0)
	v_pk_add_f32 v[80:81], v[80:81], v[240:241]
	v_pk_add_f32 v[82:83], v[82:83], v[242:243]
	v_pk_add_f32 v[84:85], v[84:85], v[244:245]
	v_pk_add_f32 v[86:87], v[86:87], v[246:247]
	v_pk_add_f32 v[88:89], v[88:89], v[152:153]
	v_pk_add_f32 v[90:91], v[90:91], v[154:155]
	v_pk_add_f32 v[92:93], v[92:93], v[156:157]
	v_pk_add_f32 v[94:95], v[94:95], v[158:159]
	ds_read2_b32 v[240:241], v223 offset0:32 offset1:33
	ds_read2_b32 v[242:243], v223 offset0:34 offset1:35
	ds_read2_b32 v[244:245], v223 offset0:40 offset1:41
	ds_read2_b32 v[246:247], v223 offset0:42 offset1:43
	ds_read2_b32 v[152:153], v223 offset0:48 offset1:49
	ds_read2_b32 v[154:155], v223 offset0:50 offset1:51
	ds_read2_b32 v[156:157], v223 offset0:56 offset1:57
	ds_read2_b32 v[158:159], v223 offset0:58 offset1:59
	s_waitcnt lgkmcnt(0)
	v_pk_add_f32 v[64:65], v[64:65], v[240:241]
	v_pk_add_f32 v[66:67], v[66:67], v[242:243]
	v_pk_add_f32 v[68:69], v[68:69], v[244:245]
	v_pk_add_f32 v[70:71], v[70:71], v[246:247]
	v_pk_add_f32 v[72:73], v[72:73], v[152:153]
	v_pk_add_f32 v[74:75], v[74:75], v[154:155]
	v_pk_add_f32 v[76:77], v[76:77], v[156:157]
	v_pk_add_f32 v[78:79], v[78:79], v[158:159]
.Lmb_pv_pe:
	ds_read_b64_tr_b16 v[240:241], v175 offset:0
	ds_read_b64_tr_b16 v[242:243], v175 offset:2048
	ds_read_b64_tr_b16 v[244:245], v175 offset:4096
	ds_read_b64_tr_b16 v[246:247], v175 offset:6144
	ds_read_b64_tr_b16 v[152:153], v175 offset:8192
	ds_read_b64_tr_b16 v[154:155], v175 offset:10240
	ds_read_b64_tr_b16 v[156:157], v175 offset:12288
	ds_read_b64_tr_b16 v[158:159], v175 offset:14336
	s_nop 5
	s_waitcnt lgkmcnt(0)
	v_mfma_f32_32x32x16_bf16 v[0:15], v[232:235], v[240:243], v[0:15]
	ds_read_b64_tr_b16 v[240:241], v175 offset:512
	ds_read_b64_tr_b16 v[242:243], v175 offset:2560
	v_mfma_f32_32x32x16_bf16 v[0:15], v[236:239], v[244:247], v[0:15]
	ds_read_b64_tr_b16 v[244:245], v175 offset:4608
	ds_read_b64_tr_b16 v[246:247], v175 offset:6656
	v_max3_f32 v254, v80, v81, v82
	v_max3_f32 v255, v83, v84, v85
	v_max3_f32 v254, v254, v86, v87
	v_max3_f32 v255, v255, v88, v89
	v_max3_f32 v254, v254, v90, v91
	v_max3_f32 v255, v255, v92, v93
	v_mfma_f32_32x32x16_bf16 v[0:15], v[144:147], v[152:155], v[0:15]
	ds_read_b64_tr_b16 v[152:153], v175 offset:8704
	ds_read_b64_tr_b16 v[154:155], v175 offset:10752
	v_max3_f32 v254, v254, v94, v95
	v_max3_f32 v255, v255, v64, v65
	v_max3_f32 v254, v254, v66, v67
	v_max3_f32 v255, v255, v68, v69
	v_max3_f32 v254, v254, v70, v71
	v_max3_f32 v255, v255, v72, v73
	v_mfma_f32_32x32x16_bf16 v[0:15], v[148:151], v[156:159], v[0:15]
	ds_read_b64_tr_b16 v[156:157], v175 offset:12800
	ds_read_b64_tr_b16 v[158:159], v175 offset:14848
	v_max3_f32 v254, v254, v74, v75
	v_max3_f32 v255, v255, v76, v77
	v_max3_f32 v254, v254, v78, v79
	v_max_f32_e32 v254, v254, v255
	v_mov_b32_e32 v255, v254
	s_waitcnt lgkmcnt(0)
	v_mfma_f32_32x32x16_bf16 v[48:63], v[232:235], v[240:243], v[48:63]
	ds_read_b64_tr_b16 v[240:241], v175 offset:1024
	ds_read_b64_tr_b16 v[242:243], v175 offset:3072
	v_permlane32_swap_b32_e32 v254, v255
	v_max_f32_e32 v254, v254, v255
	v_cmp_ge_f32_e32 vcc, s35, v254
	v_mfma_f32_32x32x16_bf16 v[48:63], v[236:239], v[244:247], v[48:63]
	ds_read_b64_tr_b16 v[244:245], v175 offset:5120
	ds_read_b64_tr_b16 v[246:247], v175 offset:7168
	v_mfma_f32_32x32x16_bf16 v[48:63], v[144:147], v[152:155], v[48:63]
	ds_read_b64_tr_b16 v[152:153], v175 offset:9216
	ds_read_b64_tr_b16 v[154:155], v175 offset:11264
	v_mfma_f32_32x32x16_bf16 v[48:63], v[148:151], v[156:159], v[48:63]
	ds_read_b64_tr_b16 v[156:157], v175 offset:13312
	ds_read_b64_tr_b16 v[158:159], v175 offset:15360
	s_waitcnt lgkmcnt(0)
	v_mfma_f32_32x32x16_bf16 v[32:47], v[232:235], v[240:243], v[32:47]
	ds_read_b64_tr_b16 v[240:241], v175 offset:1536
	ds_read_b64_tr_b16 v[242:243], v175 offset:3584
	v_mfma_f32_32x32x16_bf16 v[32:47], v[236:239], v[244:247], v[32:47]
	ds_read_b64_tr_b16 v[244:245], v175 offset:5632
	ds_read_b64_tr_b16 v[246:247], v175 offset:7680
	v_mfma_f32_32x32x16_bf16 v[32:47], v[144:147], v[152:155], v[32:47]
	ds_read_b64_tr_b16 v[152:153], v175 offset:9728
	ds_read_b64_tr_b16 v[154:155], v175 offset:11776
	v_mfma_f32_32x32x16_bf16 v[32:47], v[148:151], v[156:159], v[32:47]
	ds_read_b64_tr_b16 v[156:157], v175 offset:13824
	ds_read_b64_tr_b16 v[158:159], v175 offset:15872
	s_waitcnt lgkmcnt(0)
	v_mfma_f32_32x32x16_bf16 v[16:31], v[232:235], v[240:243], v[16:31]
	v_mfma_f32_32x32x16_bf16 v[16:31], v[236:239], v[244:247], v[16:31]
	v_mfma_f32_32x32x16_bf16 v[16:31], v[144:147], v[152:155], v[16:31]
	v_mfma_f32_32x32x16_bf16 v[16:31], v[148:151], v[156:159], v[16:31]
	s_nop 3
	s_cmp_eq_u64 vcc, exec
	s_cselect_b64 s[4:5], -1, 0
	s_cbranch_scc1 .Lmb_cm_pe
; __device__ __forceinline__ float half_max(float v) { auto rr = __builtin_amdgcn_permlane32_swap(__float_as_uint(v), __float_as_uint(v), false, false); return fmaxf(__uint_as_float(rr[0]), __uint_as_float(rr[1])); }
; __device__ __forceinline__ float half_add(float v) { auto rr = __builtin_amdgcn_permlane32_swap(__float_as_uint(v), __float_as_uint(v), false, false); return __uint_as_float(rr[0]) + __uint_as_float(rr[1]); }
; __device__ __forceinline__ void partialSM(f32x16& p0, f32x16& p1, const LAS float* tbp, int relc, float cL, float cR, float& m_reg, float& mn, float& alpha) {
;     ...
;     pmax = half_max(pmax) + cb;
;     if (__builtin_expect(__all(pmax - m_reg <= 8.f), 1)) { mn = m_reg; alpha = 1.f; }
;     else { mn = fmaxf(m_reg, pmax); alpha = __builtin_amdgcn_exp2f(m_reg - mn); m_reg = mn; }
;     const float sh = mn - cb;
; #pragma unroll
;     for (int r = 0; r < 16; ++r) { p0[r] -= sh; p1[r] -= sh; }
; #pragma unroll
;     for (int r = 0; r < 16; ++r) p0[r] = __builtin_amdgcn_exp2f(p0[r]);
; }
; __device__ __forceinline__ void finishSM(f32x16& p0, f32x16& p1, float alpha, float& l_reg, bf16x8& pa0, bf16x8& pa1, bf16x8& pa2, bf16x8& pa3) {
; #pragma unroll
;     for (int r = 0; r < 16; ++r) p1[r] = __builtin_amdgcn_exp2f(p1[r]);
;     float ps = 0;
; #pragma unroll
;     for (int r = 0; r < 16; ++r) ps += p0[r];
; #pragma unroll
;     for (int r = 0; r < 16; ++r) ps += p1[r];
;     ps = half_add(ps);
;     l_reg = l_reg * alpha + ps;
;     PK4(p0, 0, pa0); PK4(p0, 8, pa1); PK4(p1, 0, pa2); PK4(p1, 8, pa3);
; }
	v_max_f32_e32 v255, 0, v254
	v_exp_f32_e64 v251, -v255
	v_add_f32_e32 v250, v250, v255
	v_sub_f32_e32 v80, v80, v255
	v_sub_f32_e32 v81, v81, v255
	v_sub_f32_e32 v82, v82, v255
	v_sub_f32_e32 v83, v83, v255
	v_sub_f32_e32 v84, v84, v255
	v_sub_f32_e32 v85, v85, v255
	v_sub_f32_e32 v86, v86, v255
	v_sub_f32_e32 v87, v87, v255
	v_sub_f32_e32 v88, v88, v255
	v_sub_f32_e32 v89, v89, v255
	v_sub_f32_e32 v90, v90, v255
	v_sub_f32_e32 v91, v91, v255
	v_sub_f32_e32 v92, v92, v255
	v_sub_f32_e32 v93, v93, v255
	v_sub_f32_e32 v94, v94, v255
	v_sub_f32_e32 v95, v95, v255
	v_sub_f32_e32 v64, v64, v255
	v_sub_f32_e32 v65, v65, v255
	v_sub_f32_e32 v66, v66, v255
	v_sub_f32_e32 v67, v67, v255
	v_sub_f32_e32 v68, v68, v255
	v_sub_f32_e32 v69, v69, v255
	v_sub_f32_e32 v70, v70, v255
	v_sub_f32_e32 v71, v71, v255
	v_sub_f32_e32 v72, v72, v255
	v_sub_f32_e32 v73, v73, v255
	v_sub_f32_e32 v74, v74, v255
	v_sub_f32_e32 v75, v75, v255
	v_sub_f32_e32 v76, v76, v255
	v_sub_f32_e32 v77, v77, v255
	v_sub_f32_e32 v78, v78, v255
	v_sub_f32_e32 v79, v79, v255
	s_mov_b32 s29, -1
.Lmb_cm_pe:
	s_waitcnt lgkmcnt(0)
	s_barrier
	s_and_b64 vcc, exec, s[4:5]
	s_cbranch_vccnz .Lmb_nr_pe
	s_and_saveexec_b64 vcc, s[0:1]
	ds_write_b32 v215, v251 offset:128
	s_or_b64 exec, exec, vcc
	s_waitcnt lgkmcnt(0)
	ds_read_b128 v[112:115], v179 offset:224
	ds_read_b128 v[116:119], v179 offset:192
	ds_read_b128 v[120:123], v179 offset:160
	ds_read_b128 v[124:127], v179 offset:128
	s_waitcnt lgkmcnt(0)
	s_nop 3
	v_pk_mul_f32 v[14:15], v[14:15], v[114:115]
	v_pk_mul_f32 v[12:13], v[12:13], v[112:113]
	v_pk_mul_f32 v[10:11], v[10:11], v[118:119]
	v_pk_mul_f32 v[8:9], v[8:9], v[116:117]
	v_pk_mul_f32 v[6:7], v[6:7], v[122:123]
	v_pk_mul_f32 v[4:5], v[4:5], v[120:121]
	v_pk_mul_f32 v[2:3], v[2:3], v[126:127]
	v_pk_mul_f32 v[0:1], v[0:1], v[124:125]
	v_pk_mul_f32 v[62:63], v[62:63], v[114:115]
	v_pk_mul_f32 v[60:61], v[60:61], v[112:113]
	v_pk_mul_f32 v[58:59], v[58:59], v[118:119]
	v_pk_mul_f32 v[56:57], v[56:57], v[116:117]
	v_pk_mul_f32 v[54:55], v[54:55], v[122:123]
	v_pk_mul_f32 v[52:53], v[52:53], v[120:121]
	v_pk_mul_f32 v[50:51], v[50:51], v[126:127]
	v_pk_mul_f32 v[48:49], v[48:49], v[124:125]
	v_pk_mul_f32 v[46:47], v[46:47], v[114:115]
	v_pk_mul_f32 v[44:45], v[44:45], v[112:113]
	v_pk_mul_f32 v[42:43], v[42:43], v[118:119]
	v_pk_mul_f32 v[40:41], v[40:41], v[116:117]
	v_pk_mul_f32 v[38:39], v[38:39], v[122:123]
	v_pk_mul_f32 v[36:37], v[36:37], v[120:121]
	v_pk_mul_f32 v[34:35], v[34:35], v[126:127]
	v_pk_mul_f32 v[32:33], v[32:33], v[124:125]
	v_pk_mul_f32 v[30:31], v[30:31], v[114:115]
	v_pk_mul_f32 v[28:29], v[28:29], v[112:113]
	v_pk_mul_f32 v[26:27], v[26:27], v[118:119]
	v_pk_mul_f32 v[24:25], v[24:25], v[116:117]
	v_pk_mul_f32 v[22:23], v[22:23], v[122:123]
	v_pk_mul_f32 v[20:21], v[20:21], v[120:121]
	v_pk_mul_f32 v[18:19], v[18:19], v[126:127]
	v_pk_mul_f32 v[16:17], v[16:17], v[124:125]
.Lmb_nr_pe:
	v_exp_f32_e32 v80, v80
	v_exp_f32_e32 v81, v81
	v_exp_f32_e32 v82, v82
	v_exp_f32_e32 v83, v83
	v_exp_f32_e32 v84, v84
	v_exp_f32_e32 v85, v85
	v_exp_f32_e32 v86, v86
	v_exp_f32_e32 v87, v87
	v_exp_f32_e32 v88, v88
	v_exp_f32_e32 v89, v89
	v_exp_f32_e32 v90, v90
	v_exp_f32_e32 v91, v91
	v_exp_f32_e32 v92, v92
	v_exp_f32_e32 v93, v93
	v_exp_f32_e32 v94, v94
	v_exp_f32_e32 v95, v95
	v_exp_f32_e32 v64, v64
	v_exp_f32_e32 v65, v65
	v_exp_f32_e32 v66, v66
	v_exp_f32_e32 v67, v67
	v_exp_f32_e32 v68, v68
	v_exp_f32_e32 v69, v69
	v_exp_f32_e32 v70, v70
	v_exp_f32_e32 v71, v71
	v_exp_f32_e32 v72, v72
	v_exp_f32_e32 v73, v73
	v_exp_f32_e32 v74, v74
	v_exp_f32_e32 v75, v75
	v_exp_f32_e32 v76, v76
	v_exp_f32_e32 v77, v77
	v_exp_f32_e32 v78, v78
	v_exp_f32_e32 v79, v79
	v_add_f32_e32 v254, v80, v81
	v_add_f32_e32 v255, v82, v83
	v_add_f32_e32 v254, v254, v84
	v_add_f32_e32 v255, v255, v85
	v_add_f32_e32 v254, v254, v86
	v_add_f32_e32 v255, v255, v87
	v_add_f32_e32 v254, v254, v88
	v_add_f32_e32 v255, v255, v89
	v_add_f32_e32 v254, v254, v90
	v_add_f32_e32 v255, v255, v91
	v_add_f32_e32 v254, v254, v92
	v_add_f32_e32 v255, v255, v93
	v_add_f32_e32 v254, v254, v94
	v_add_f32_e32 v255, v255, v95
	v_add_f32_e32 v254, v254, v64
	v_add_f32_e32 v255, v255, v65
	v_add_f32_e32 v254, v254, v66
	v_add_f32_e32 v255, v255, v67
	v_add_f32_e32 v254, v254, v68
	v_add_f32_e32 v255, v255, v69
	v_add_f32_e32 v254, v254, v70
	v_add_f32_e32 v255, v255, v71
	v_add_f32_e32 v254, v254, v72
	v_add_f32_e32 v255, v255, v73
	v_add_f32_e32 v254, v254, v74
	v_add_f32_e32 v255, v255, v75
	v_add_f32_e32 v254, v254, v76
	v_add_f32_e32 v255, v255, v77
	v_add_f32_e32 v254, v254, v78
	v_add_f32_e32 v255, v255, v79
	v_add_f32_e32 v254, v254, v255
	v_mov_b32_e32 v255, v254
	v_cvt_pk_bf16_f32 v80, v80, v81
	v_cvt_pk_bf16_f32 v81, v82, v83
	v_cvt_pk_bf16_f32 v82, v84, v85
	v_cvt_pk_bf16_f32 v83, v86, v87
	v_cvt_pk_bf16_f32 v84, v88, v89
	v_cvt_pk_bf16_f32 v85, v90, v91
	v_cvt_pk_bf16_f32 v86, v92, v93
	v_cvt_pk_bf16_f32 v87, v94, v95
	v_permlane32_swap_b32_e32 v254, v255
	v_cvt_pk_bf16_f32 v64, v64, v65
	v_cvt_pk_bf16_f32 v65, v66, v67
	v_cvt_pk_bf16_f32 v66, v68, v69
	v_cvt_pk_bf16_f32 v67, v70, v71
	v_cvt_pk_bf16_f32 v68, v72, v73
	v_cvt_pk_bf16_f32 v69, v74, v75
	v_cvt_pk_bf16_f32 v70, v76, v77
	v_cvt_pk_bf16_f32 v71, v78, v79
	v_add_f32_e32 v254, v254, v255
	v_fma_f32 v216, v216, v251, v254
	v_permlane32_swap_b32_e32 v80, v82
	v_permlane32_swap_b32_e32 v81, v83
	v_permlane32_swap_b32_e32 v84, v86
	v_permlane32_swap_b32_e32 v85, v87
	v_permlane32_swap_b32_e32 v64, v66
	v_permlane32_swap_b32_e32 v65, v67
	v_permlane32_swap_b32_e32 v68, v70
	v_permlane32_swap_b32_e32 v69, v71
	ds_read_b64_tr_b16 v[88:89], v186 offset:0
	ds_read_b64_tr_b16 v[90:91], v186 offset:2048
	ds_read_b64_tr_b16 v[92:93], v186 offset:4096
	ds_read_b64_tr_b16 v[94:95], v186 offset:6144
	ds_read_b64_tr_b16 v[72:73], v186 offset:8192
	ds_read_b64_tr_b16 v[74:75], v186 offset:10240
	ds_read_b64_tr_b16 v[76:77], v186 offset:12288
	ds_read_b64_tr_b16 v[78:79], v186 offset:14336
	s_waitcnt lgkmcnt(0)
; #define LAS __attribute__((address_space(3)))
; #define LDS_WAIT() asm volatile("s_waitcnt lgkmcnt(0)" ::: "memory")
; __device__ __forceinline__ int crow(int r, int hi) { return (r & 3) + 8 * (r >> 2) + 4 * hi; }
; template <int OFF> __device__ __forceinline__ s16x4 tr_read(int vb) { s16x4 r; asm volatile("ds_read_b64_tr_b16 %0, %1 offset:%2" : "=&v"(r) : "v"(vb), "i"(OFF) : "memory"); return r; }
; template <int D0> __device__ __forceinline__ void pv_one(f32x16& od, int vb, bf16x8 pa0, bf16x8 pa1, bf16x8 pa2, bf16x8 pa3) {
;     s16x4 l0 = tr_read<v_rd_off(D0, 0, 0)>(vb), h0 = tr_read<v_rd_off(D0, 0, 1)>(vb), l1 = tr_read<v_rd_off(D0, 1, 0)>(vb), h1 = tr_read<v_rd_off(D0, 1, 1)>(vb);
;     s16x4 l2 = tr_read<v_rd_off(D0, 2, 0)>(vb), h2 = tr_read<v_rd_off(D0, 2, 1)>(vb), l3 = tr_read<v_rd_off(D0, 3, 0)>(vb), h3 = tr_read<v_rd_off(D0, 3, 1)>(vb);
;     asm volatile("s_waitcnt lgkmcnt(0)" : "+v"(l0), "+v"(h0), "+v"(l1), "+v"(h1), "+v"(l2), "+v"(h2), "+v"(l3), "+v"(h3) :: "memory");
;     od = __builtin_amdgcn_mfma_f32_32x32x16_bf16(pa0, PKV(l0, h0), od, 0, 0, 0);
;     od = __builtin_amdgcn_mfma_f32_32x32x16_bf16(pa1, PKV(l1, h1), od, 0, 0, 0);
;     od = __builtin_amdgcn_mfma_f32_32x32x16_bf16(pa2, PKV(l2, h2), od, 0, 0, 0);
;     od = __builtin_amdgcn_mfma_f32_32x32x16_bf16(pa3, PKV(l3, h3), od, 0, 0, 0);
; __device__ __forceinline__ void unit(LAS unsigned char* lds, const bf16* __restrict__ PROJ, bf16* __restrict__ MIXED, const float* __restrict__ subln_g, float lam, int R0, int seq, int h, int qb) {
;     ...
;     if (hi == 0) li_l[r32] = l_reg; LDS_WAIT();
;     float rli[16];
; #pragma unroll
;     for (int r = 0; r < 16; ++r) rli[r] = __builtin_amdgcn_rcpf(li_l[crow(r, hi)]);
;     __syncthreads();
;     LAS float* xch = (LAS float*)lds + g * 4096;
;     if (c == 1) {
; #pragma unroll
;         for (int d = 0; d < 4; ++d)
; #pragma unroll
;             for (int r = 0; r < 16; ++r) xch[(d * 16 + r) * 64 + lane] = o[d][r] * rli[r]; }
	v_mfma_f32_32x32x16_bf16 v[0:15], v[80:83], v[88:91], v[0:15]
	ds_read_b64_tr_b16 v[88:89], v186 offset:512
	ds_read_b64_tr_b16 v[90:91], v186 offset:2560
	v_mfma_f32_32x32x16_bf16 v[0:15], v[84:87], v[92:95], v[0:15]
	ds_read_b64_tr_b16 v[92:93], v186 offset:4608
	ds_read_b64_tr_b16 v[94:95], v186 offset:6656
	v_mfma_f32_32x32x16_bf16 v[0:15], v[64:67], v[72:75], v[0:15]
	ds_read_b64_tr_b16 v[72:73], v186 offset:8704
	ds_read_b64_tr_b16 v[74:75], v186 offset:10752
	v_mfma_f32_32x32x16_bf16 v[0:15], v[68:71], v[76:79], v[0:15]
	ds_read_b64_tr_b16 v[76:77], v186 offset:12800
	ds_read_b64_tr_b16 v[78:79], v186 offset:14848
	s_waitcnt lgkmcnt(0)
	v_mfma_f32_32x32x16_bf16 v[48:63], v[80:83], v[88:91], v[48:63]
	ds_read_b64_tr_b16 v[88:89], v186 offset:1024
	ds_read_b64_tr_b16 v[90:91], v186 offset:3072
	v_mfma_f32_32x32x16_bf16 v[48:63], v[84:87], v[92:95], v[48:63]
	ds_read_b64_tr_b16 v[92:93], v186 offset:5120
	ds_read_b64_tr_b16 v[94:95], v186 offset:7168
	v_mfma_f32_32x32x16_bf16 v[48:63], v[64:67], v[72:75], v[48:63]
	ds_read_b64_tr_b16 v[72:73], v186 offset:9216
	ds_read_b64_tr_b16 v[74:75], v186 offset:11264
	v_mfma_f32_32x32x16_bf16 v[48:63], v[68:71], v[76:79], v[48:63]
	ds_read_b64_tr_b16 v[76:77], v186 offset:13312
	ds_read_b64_tr_b16 v[78:79], v186 offset:15360
	s_waitcnt lgkmcnt(0)
	v_mfma_f32_32x32x16_bf16 v[32:47], v[80:83], v[88:91], v[32:47]
	ds_read_b64_tr_b16 v[88:89], v186 offset:1536
	ds_read_b64_tr_b16 v[90:91], v186 offset:3584
	v_mfma_f32_32x32x16_bf16 v[32:47], v[84:87], v[92:95], v[32:47]
	ds_read_b64_tr_b16 v[92:93], v186 offset:5632
	ds_read_b64_tr_b16 v[94:95], v186 offset:7680
	v_mfma_f32_32x32x16_bf16 v[32:47], v[64:67], v[72:75], v[32:47]
	ds_read_b64_tr_b16 v[72:73], v186 offset:9728
	ds_read_b64_tr_b16 v[74:75], v186 offset:11776
	v_mfma_f32_32x32x16_bf16 v[32:47], v[68:71], v[76:79], v[32:47]
	ds_read_b64_tr_b16 v[76:77], v186 offset:13824
	ds_read_b64_tr_b16 v[78:79], v186 offset:15872
	s_waitcnt lgkmcnt(0)
	v_mfma_f32_32x32x16_bf16 v[16:31], v[80:83], v[88:91], v[16:31]
	v_mfma_f32_32x32x16_bf16 v[16:31], v[84:87], v[92:95], v[16:31]
	v_mfma_f32_32x32x16_bf16 v[16:31], v[64:67], v[72:75], v[16:31]
	v_mfma_f32_32x32x16_bf16 v[16:31], v[68:71], v[76:79], v[16:31]
	s_and_saveexec_b64 s[4:5], s[0:1]
	ds_write_b32 v215, v216
	s_or_b64 exec, exec, s[4:5]
	s_waitcnt lgkmcnt(0)
	ds_read_b128 v[64:67], v179
	ds_read_b128 v[68:71], v179 offset:32
	s_lshl_b32 s4, s95, 14
	s_add_i32 s6, s4, 0
	s_cmp_eq_u32 s71, 0
	s_waitcnt lgkmcnt(1)
	v_rcp_f32_e32 v80, v64
	v_rcp_f32_e32 v79, v65
	v_rcp_f32_e32 v78, v66
	v_rcp_f32_e32 v102, v67
	s_waitcnt lgkmcnt(0)
	v_rcp_f32_e32 v107, v68
	ds_read_b128 v[64:67], v179 offset:64
	v_rcp_f32_e32 v106, v69
	v_rcp_f32_e32 v105, v70
	v_rcp_f32_e32 v104, v71
	ds_read_b128 v[68:71], v179 offset:96
	s_waitcnt lgkmcnt(1)
	v_rcp_f32_e32 v97, v64
	v_rcp_f32_e32 v96, v65
	v_rcp_f32_e32 v95, v66
	v_rcp_f32_e32 v94, v67
	s_waitcnt lgkmcnt(0)
	v_rcp_f32_e32 v93, v68
	v_rcp_f32_e32 v92, v69
	v_rcp_f32_e32 v91, v70
	v_rcp_f32_e32 v90, v71
	s_cselect_b64 s[4:5], -1, 0
	s_and_b64 vcc, exec, s[4:5]
	v_lshl_add_u32 v98, v190, 2, s6
	s_barrier
	s_cbranch_vccnz .LBB0_294
	v_mul_f32_e32 v64, v0, v80
	v_mul_f32_e32 v65, v1, v79
	ds_write2st64_b32 v98, v64, v65 offset1:1
	v_mul_f32_e32 v64, v2, v78
	v_mul_f32_e32 v65, v3, v102
	ds_write2st64_b32 v98, v64, v65 offset0:2 offset1:3
	v_mul_f32_e32 v64, v4, v107
	v_mul_f32_e32 v65, v5, v106
	ds_write2st64_b32 v98, v64, v65 offset0:4 offset1:5
	v_mul_f32_e32 v64, v6, v105
	v_mul_f32_e32 v65, v7, v104
	ds_write2st64_b32 v98, v64, v65 offset0:6 offset1:7
	v_mul_f32_e32 v64, v8, v97
	v_mul_f32_e32 v65, v9, v96
	ds_write2st64_b32 v98, v64, v65 offset0:8 offset1:9
	v_mul_f32_e32 v64, v10, v95
	v_mul_f32_e32 v65, v11, v94
	ds_write2st64_b32 v98, v64, v65 offset0:10 offset1:11
	v_mul_f32_e32 v64, v12, v93
	v_mul_f32_e32 v65, v13, v92
	ds_write2st64_b32 v98, v64, v65 offset0:12 offset1:13
	v_mul_f32_e32 v64, v14, v91
	v_mul_f32_e32 v65, v15, v90
	ds_write2st64_b32 v98, v64, v65 offset0:14 offset1:15
	v_mul_f32_e32 v64, v48, v80
	v_mul_f32_e32 v65, v49, v79
	ds_write2st64_b32 v98, v64, v65 offset0:16 offset1:17
	v_mul_f32_e32 v64, v50, v78
	v_mul_f32_e32 v65, v51, v102
	ds_write2st64_b32 v98, v64, v65 offset0:18 offset1:19
	v_mul_f32_e32 v64, v52, v107
	v_mul_f32_e32 v65, v53, v106
	ds_write2st64_b32 v98, v64, v65 offset0:20 offset1:21
	v_mul_f32_e32 v64, v54, v105
	v_mul_f32_e32 v65, v55, v104
	ds_write2st64_b32 v98, v64, v65 offset0:22 offset1:23
	v_mul_f32_e32 v64, v56, v97
	v_mul_f32_e32 v65, v57, v96
	ds_write2st64_b32 v98, v64, v65 offset0:24 offset1:25
	v_mul_f32_e32 v64, v58, v95
	v_mul_f32_e32 v65, v59, v94
	ds_write2st64_b32 v98, v64, v65 offset0:26 offset1:27
	v_mul_f32_e32 v64, v60, v93
	v_mul_f32_e32 v65, v61, v92
	ds_write2st64_b32 v98, v64, v65 offset0:28 offset1:29
	v_mul_f32_e32 v64, v62, v91
	v_mul_f32_e32 v65, v63, v90
	ds_write2st64_b32 v98, v64, v65 offset0:30 offset1:31
	v_mul_f32_e32 v64, v32, v80
	v_mul_f32_e32 v65, v33, v79
	ds_write2st64_b32 v98, v64, v65 offset0:32 offset1:33
	v_mul_f32_e32 v64, v34, v78
	v_mul_f32_e32 v65, v35, v102
	ds_write2st64_b32 v98, v64, v65 offset0:34 offset1:35
	v_mul_f32_e32 v64, v36, v107
	v_mul_f32_e32 v65, v37, v106
	ds_write2st64_b32 v98, v64, v65 offset0:36 offset1:37
	v_mul_f32_e32 v64, v38, v105
	v_mul_f32_e32 v65, v39, v104
	ds_write2st64_b32 v98, v64, v65 offset0:38 offset1:39
	v_mul_f32_e32 v64, v40, v97
	v_mul_f32_e32 v65, v41, v96
	ds_write2st64_b32 v98, v64, v65 offset0:40 offset1:41
	v_mul_f32_e32 v64, v42, v95
	v_mul_f32_e32 v65, v43, v94
	ds_write2st64_b32 v98, v64, v65 offset0:42 offset1:43
	v_mul_f32_e32 v64, v44, v93
	v_mul_f32_e32 v65, v45, v92
	ds_write2st64_b32 v98, v64, v65 offset0:44 offset1:45
	v_mul_f32_e32 v64, v46, v91
	v_mul_f32_e32 v65, v47, v90
	ds_write2st64_b32 v98, v64, v65 offset0:46 offset1:47
	v_mul_f32_e32 v64, v16, v80
	v_mul_f32_e32 v65, v17, v79
	ds_write2st64_b32 v98, v64, v65 offset0:48 offset1:49
	v_mul_f32_e32 v64, v18, v78
	v_mul_f32_e32 v65, v19, v102
	ds_write2st64_b32 v98, v64, v65 offset0:50 offset1:51
	v_mul_f32_e32 v64, v20, v107
	v_mul_f32_e32 v65, v21, v106
	ds_write2st64_b32 v98, v64, v65 offset0:52 offset1:53
	v_mul_f32_e32 v64, v22, v105
	v_mul_f32_e32 v65, v23, v104
	ds_write2st64_b32 v98, v64, v65 offset0:54 offset1:55
	v_mul_f32_e32 v64, v24, v97
	v_mul_f32_e32 v65, v25, v96
	ds_write2st64_b32 v98, v64, v65 offset0:56 offset1:57
	v_mul_f32_e32 v64, v26, v95
	v_mul_f32_e32 v65, v27, v94
	ds_write2st64_b32 v98, v64, v65 offset0:58 offset1:59
	v_mul_f32_e32 v64, v28, v93
	v_mul_f32_e32 v65, v29, v92
	ds_write2st64_b32 v98, v64, v65 offset0:60 offset1:61
	v_mul_f32_e32 v64, v30, v91
	v_mul_f32_e32 v65, v31, v90
	ds_write2st64_b32 v98, v64, v65 offset0:62 offset1:63
